# a_up epilogue (srow + rope loads) and L9 EpiGate epilogue (16 gate loads) hoisted into one burst at tile-epilogue start instead of serialized load+vmcnt(0) per row group
# speedup vs baseline: 1.0121x; 1.0006x over previous
; DI unsigned cvtpk(float lo, float hi) { unsigned r; asm volatile("v_cvt_pk_bf16_f32 %0, %1, %2" : "=v"(r) : "v"(lo), "v"(hi)); return r; }
; DI bf16_t f2bf(float f) { return (bf16_t)(cvtpk(f, 0.f) & 0xffffu); }
; DI void rope128(f32x4& v0, f32x4& v1, const float* ropeA, int pos, int fq) {
;   const f32x4 cs = *(const f32x4*)(ropeA + pos * 32 + 4 * fq), sn = *(const f32x4*)(ropeA + pos * 32 + 16 + 4 * fq);
; #pragma unroll
;   for (int j = 0; j < 4; ++j) { const float x1 = v0[j], x2 = v1[j]; v0[j] = x1 * cs[j] - x2 * sn[j]; v1[j] = x2 * cs[j] + x1 * sn[j]; }
; }
; DI void store_vt(bf16_t* base  , int d0, int pos, const f32x4& v) {
; #pragma unroll
;   for (int j = 0; j < 4; ++j) base[(size_t)(d0 + j) * SL + pos] = f2bf(v[j]);
;   DI void operator()(const AccT& acc, const Unit& u, int wr, int wc, int fr, int fq) const {
;     ...
;           const int row = u.pm * BM + ai * HALF + wr * 64 + m * 16 + fr, pos = row & (SL - 1), b = row >> 12;
;           const float s = srow[row];
;           f32x4 v0 = acc[ai][bj][m][0] * s, v1 = acc[ai][bj][m][1] * s;
;           const int cin = wc * 32 + 4 * fq;
;           if (cb < 8) { if (wc == 0) rope128(v0, v1, ropeA, pos, fq);
;             bf16_t* dp = ak + (size_t)row * 1024 + cb * 128 + cin;
;             *(u32x2*)dp = (u32x2){cvtpk(v0[0], v0[1]), cvtpk(v0[2], v0[3])}; *(u32x2*)(dp + 16) = (u32x2){cvtpk(v1[0], v1[1]), cvtpk(v1[2], v1[3])}; }
;           else { bf16_t* base = avT + (size_t)((b * 8 + (cb - 8)) * 128) * SL; store_vt(base, cin, pos, v0); store_vt(base, cin + 16, pos, v1); }
.LBB0_826:
	s_lshl_b32 s42, s24, 8
	s_lshl_b32 s13, s4, 1
	s_add_i32 s42, s42, s34
	s_cmp_gt_i32 s4, 3
	s_cselect_b64 s[22:23], -1, 0
	s_ashr_i32 s0, s42, 9
	s_add_i32 s41, s13, -8
	s_and_b32 s40, s0, -8
	s_add_i32 s0, s40, s41
	s_lshl_b32 s0, s0, 7
	s_ashr_i32 s1, s0, 31
	v_or_b32_e32 v146, s42, v139
	s_lshl_b64 s[20:21], s[0:1], 13
	v_readlane_b32 s0, v250, 56
	v_ashrrev_i32_e32 v147, 31, v146
	v_readlane_b32 s1, v250, 57
	v_mov_b32_e32 v0, 0xfcf
	v_bitop3_b32 v155, s42, v0, v139 bitop3:0xc8
	v_lshl_add_u64 v[148:149], v[146:147], 2, s[0:1]
	global_load_dword v213, v[148:149], off
	global_load_dword v218, v[148:149], off offset:64
	global_load_dword v219, v[148:149], off offset:128
	global_load_dword v223, v[148:149], off offset:192
	global_load_dword v228, v[148:149], off offset:512
	global_load_dword v231, v[148:149], off offset:576
	global_load_dword v244, v[148:149], off offset:640
	global_load_dword v245, v[148:149], off offset:704
	s_cmp_lg_u64 s[22:23], 0
	s_cbranch_scc1 .Lap_done
	s_cmp_eq_u64 s[10:11], 0
	s_cbranch_scc1 .Lap_done
	v_lshlrev_b32_e32 v0, 7, v155
	v_lshl_add_u64 v[246:247], v[140:141], 0, v[0:1]
	global_load_dwordx4 v[168:171], v[246:247], off
	global_load_dwordx4 v[172:175], v[246:247], off offset:64
	global_load_dwordx4 v[176:179], v[246:247], off offset:2048
	global_load_dwordx4 v[180:183], v[246:247], off offset:2112
	s_mov_b64 s[0:1], 0x1000
	v_lshl_add_u64 v[246:247], v[246:247], 0, s[0:1]
	global_load_dwordx4 v[184:187], v[246:247], off
	global_load_dwordx4 v[188:191], v[246:247], off offset:64
	global_load_dwordx4 v[192:195], v[246:247], off offset:2048
	global_load_dwordx4 v[196:199], v[246:247], off offset:2112
	s_mov_b64 s[0:1], 0x3000
	v_lshl_add_u64 v[246:247], v[246:247], 0, s[0:1]
	global_load_dwordx4 v[200:203], v[246:247], off
	global_load_dwordx4 v[204:207], v[246:247], off offset:64
	global_load_dwordx4 v[208:211], v[246:247], off offset:2048
	global_load_dwordx4 v[214:217], v[246:247], off offset:2112
	s_mov_b64 s[0:1], 0x1000
	v_lshl_add_u64 v[246:247], v[246:247], 0, s[0:1]
	global_load_dwordx4 v[224:227], v[246:247], off
	global_load_dwordx4 v[232:235], v[246:247], off offset:64
	global_load_dwordx4 v[236:239], v[246:247], off offset:2048
	global_load_dwordx4 v[240:243], v[246:247], off offset:2112
.Lap_done:
	s_waitcnt vmcnt(0)
	v_mov_b32_e32 v0, v213
	s_mov_b64 s[0:1], -1
	s_and_b64 vcc, exec, s[22:23]
	v_pk_mul_f32 v[128:129], v[128:129], v[0:1] op_sel_hi:[1,0]
	v_pk_mul_f32 v[150:151], v[126:127], v[0:1] op_sel_hi:[1,0]
	v_pk_mul_f32 v[126:127], v[124:125], v[0:1] op_sel_hi:[1,0]
	v_pk_mul_f32 v[122:123], v[122:123], v[0:1] op_sel_hi:[1,0]
	v_or_b32_e32 v0, v155, v153
	v_lshlrev_b32_e32 v124, 1, v0
	s_cbranch_vccz .LBB0_828
	v_readlane_b32 s0, v251, 0
	s_add_u32 s0, s0, s20
	v_readlane_b32 s1, v251, 1
	s_addc_u32 s1, s1, s21
	v_mov_b32_e32 v125, v1
	v_cvt_pk_bf16_f32 v0, v150, v1
	v_lshl_add_u64 v[156:157], s[0:1], 0, v[124:125]
	s_nop 1
	global_store_short v124, v0, s[0:1]
	s_movk_i32 s0, 0x2000
	v_add_co_u32_e32 v158, vcc, s0, v156
	v_cvt_pk_bf16_f32 v0, v151, v1
	s_movk_i32 s0, 0x6000
	s_nop 0
	v_addc_co_u32_e32 v159, vcc, 0, v157, vcc
	global_store_short v[158:159], v0, off
	v_add_co_u32_e32 v158, vcc, s82, v156
	v_cvt_pk_bf16_f32 v0, v128, v1
	s_nop 1
	v_addc_co_u32_e32 v159, vcc, 0, v157, vcc
	global_store_short v[158:159], v0, off
	v_add_co_u32_e32 v158, vcc, s0, v156
	s_mov_b32 s0, 0x20000
	s_nop 0
	v_addc_co_u32_e32 v159, vcc, 0, v157, vcc
	v_cvt_pk_bf16_f32 v0, v129, v1
	global_store_short v[158:159], v0, off
	v_add_co_u32_e32 v158, vcc, s0, v156
	s_mov_b32 s0, 0x22000
	s_nop 0
	v_addc_co_u32_e32 v159, vcc, 0, v157, vcc
	v_cvt_pk_bf16_f32 v0, v122, v1
	global_store_short v[158:159], v0, off
	v_add_co_u32_e32 v158, vcc, s0, v156
	v_cvt_pk_bf16_f32 v0, v123, v1
	s_mov_b64 s[0:1], 0
	s_nop 0
	v_addc_co_u32_e32 v159, vcc, 0, v157, vcc
	global_store_short v[158:159], v0, off
	v_add_co_u32_e32 v158, vcc, 0x24000, v156
	v_cvt_pk_bf16_f32 v0, v126, v1
	s_nop 1
	v_addc_co_u32_e32 v159, vcc, 0, v157, vcc
	v_add_co_u32_e32 v156, vcc, 0x26000, v156
	global_store_short v[158:159], v0, off
	s_nop 0
	v_addc_co_u32_e32 v157, vcc, 0, v157, vcc
	v_cvt_pk_bf16_f32 v0, v127, v1
	global_store_short v[156:157], v0, off
.LBB0_828:
	s_lshl_b32 s18, s4, 8
	v_cndmask_b32_e64 v0, 0, 1, s[10:11]
	s_ashr_i32 s19, s18, 31
	s_andn2_b64 vcc, exec, s[0:1]
	v_cmp_ne_u32_e64 s[0:1], 1, v0
	v_mov_b32_e32 v212, v220
	s_cbranch_vccnz .LBB0_832
	s_and_b64 vcc, exec, s[0:1]
	s_cbranch_vccnz .LBB0_831
	v_lshlrev_b32_e32 v0, 7, v155
	v_lshl_add_u64 v[160:161], v[140:141], 0, v[0:1]
	v_mov_b32_e32 v156, v168
	v_mov_b32_e32 v157, v169
	v_mov_b32_e32 v158, v170
	v_mov_b32_e32 v159, v171
	v_mov_b32_e32 v160, v172
	v_mov_b32_e32 v161, v173
	v_mov_b32_e32 v162, v174
	v_mov_b32_e32 v163, v175
	v_pk_mul_f32 v[164:165], v[122:123], v[160:161]
	s_nop 0
	v_pk_fma_f32 v[164:165], v[150:151], v[156:157], v[164:165] neg_lo:[0,0,1] neg_hi:[0,0,1]
	v_pk_mul_f32 v[150:151], v[150:151], v[160:161]
	v_mul_f32_e32 v160, v128, v162
	v_pk_fma_f32 v[122:123], v[122:123], v[156:157], v[150:151]
	v_mul_f32_e32 v150, v128, v158
	v_mul_f32_e32 v156, v126, v162
	v_mul_f32_e32 v158, v126, v158
	v_mov_b32_e32 v126, v129
	v_mov_b32_e32 v162, v159
	v_pk_mul_f32 v[166:167], v[126:127], v[162:163]
	v_mov_b32_e32 v128, v127
	v_mov_b32_e32 v151, v166
	v_mov_b32_e32 v157, v167
	v_pk_mul_f32 v[126:127], v[128:129], v[162:163]
	v_pk_add_f32 v[156:157], v[150:151], v[156:157] neg_lo:[0,1] neg_hi:[0,1]
	v_mov_b32_e32 v159, v126
	v_mov_b32_e32 v161, v127
	v_pk_add_f32 v[126:127], v[158:159], v[160:161]
	v_mov_b32_e32 v150, v164
	v_mov_b32_e32 v151, v165
	v_mov_b32_e32 v128, v156
	v_mov_b32_e32 v129, v157

; DI unsigned cvtpk(float lo, float hi) { unsigned r; asm volatile("v_cvt_pk_bf16_f32 %0, %1, %2" : "=v"(r) : "v"(lo), "v"(hi)); return r; }
; DI bf16_t f2bf(float f) { return (bf16_t)(cvtpk(f, 0.f) & 0xffffu); }
; DI void rope128(f32x4& v0, f32x4& v1, const float* ropeA, int pos, int fq) {
;   const f32x4 cs = *(const f32x4*)(ropeA + pos * 32 + 4 * fq), sn = *(const f32x4*)(ropeA + pos * 32 + 16 + 4 * fq);
; #pragma unroll
;   for (int j = 0; j < 4; ++j) { const float x1 = v0[j], x2 = v1[j]; v0[j] = x1 * cs[j] - x2 * sn[j]; v1[j] = x2 * cs[j] + x1 * sn[j]; }
; }
; DI void store_vt(bf16_t* base  , int d0, int pos, const f32x4& v) {
; #pragma unroll
;   for (int j = 0; j < 4; ++j) base[(size_t)(d0 + j) * SL + pos] = f2bf(v[j]);
;   DI void operator()(const AccT& acc, const Unit& u, int wr, int wc, int fr, int fq) const {
;     ...
;           const float s = srow[row];
;           f32x4 v0 = acc[ai][bj][m][0] * s, v1 = acc[ai][bj][m][1] * s;
;           const int cin = wc * 32 + 4 * fq;
;           if (cb < 8) { if (wc == 0) rope128(v0, v1, ropeA, pos, fq);
;             bf16_t* dp = ak + (size_t)row * 1024 + cb * 128 + cin;
;             *(u32x2*)dp = (u32x2){cvtpk(v0[0], v0[1]), cvtpk(v0[2], v0[3])}; *(u32x2*)(dp + 16) = (u32x2){cvtpk(v1[0], v1[1]), cvtpk(v1[2], v1[3])}; }
;           else { bf16_t* base = avT + (size_t)((b * 8 + (cb - 8)) * 128) * SL; store_vt(base, cin, pos, v0); store_vt(base, cin + 16, pos, v1); }
.LBB0_832:
	s_movk_i32 s4, 0xfdf
	v_or_b32_e32 v122, 16, v146
	v_bitop3_b32 v150, v146, s4, 16 bitop3:0xc8
	v_readlane_b32 s4, v250, 56
	v_ashrrev_i32_e32 v123, 31, v122
	v_readlane_b32 s5, v250, 57
	s_mov_b64 s[24:25], -1
	s_andn2_b64 vcc, exec, s[22:23]
	v_lshl_add_u64 v[126:127], v[122:123], 2, s[4:5]
	v_mov_b32_e32 v0, v218
	v_pk_mul_f32 v[120:121], v[120:121], v[0:1] op_sel_hi:[1,0]
	v_pk_mul_f32 v[128:129], v[118:119], v[0:1] op_sel_hi:[1,0]
	v_pk_mul_f32 v[118:119], v[116:117], v[0:1] op_sel_hi:[1,0]
	v_pk_mul_f32 v[114:115], v[114:115], v[0:1] op_sel_hi:[1,0]
	v_cndmask_b32_e64 v0, 0, 1, s[22:23]
	v_cmp_ne_u32_e64 s[4:5], 1, v0
	v_or_b32_e32 v0, v150, v153
	v_lshlrev_b32_e32 v116, 1, v0
	s_cbranch_vccnz .LBB0_834
	v_readlane_b32 s22, v251, 0
	s_add_u32 s22, s22, s20
	v_readlane_b32 s23, v251, 1
	s_addc_u32 s23, s23, s21
	v_mov_b32_e32 v117, v1
	v_cvt_pk_bf16_f32 v0, v128, v1
	v_lshl_add_u64 v[156:157], s[22:23], 0, v[116:117]
	s_mov_b64 s[24:25], 0
	s_nop 0
	global_store_short v116, v0, s[22:23]
	s_movk_i32 s22, 0x2000
	v_add_co_u32_e32 v158, vcc, s22, v156
	v_cvt_pk_bf16_f32 v0, v129, v1
	s_movk_i32 s22, 0x6000
	s_nop 0
	v_addc_co_u32_e32 v159, vcc, 0, v157, vcc
	global_store_short v[158:159], v0, off
	v_add_co_u32_e32 v158, vcc, s82, v156
	v_cvt_pk_bf16_f32 v0, v120, v1
	s_nop 1
	v_addc_co_u32_e32 v159, vcc, 0, v157, vcc
	global_store_short v[158:159], v0, off
	v_add_co_u32_e32 v158, vcc, s22, v156
	s_mov_b32 s22, 0x20000
	s_nop 0
	v_addc_co_u32_e32 v159, vcc, 0, v157, vcc
	v_cvt_pk_bf16_f32 v0, v121, v1
	global_store_short v[158:159], v0, off
	v_add_co_u32_e32 v158, vcc, s22, v156
	s_mov_b32 s22, 0x22000
	s_nop 0
	v_addc_co_u32_e32 v159, vcc, 0, v157, vcc
	v_cvt_pk_bf16_f32 v0, v114, v1
	global_store_short v[158:159], v0, off
	v_add_co_u32_e32 v158, vcc, s22, v156
	v_cvt_pk_bf16_f32 v0, v115, v1
	s_nop 1
	v_addc_co_u32_e32 v159, vcc, 0, v157, vcc
	global_store_short v[158:159], v0, off
	v_add_co_u32_e32 v158, vcc, 0x24000, v156
	v_cvt_pk_bf16_f32 v0, v118, v1
	s_nop 1
	v_addc_co_u32_e32 v159, vcc, 0, v157, vcc
	v_add_co_u32_e32 v156, vcc, 0x26000, v156
	global_store_short v[158:159], v0, off
	s_nop 0
	v_addc_co_u32_e32 v157, vcc, 0, v157, vcc
	v_cvt_pk_bf16_f32 v0, v119, v1
	global_store_short v[156:157], v0, off
.LBB0_834:
	s_andn2_b64 vcc, exec, s[24:25]
	s_cbranch_vccnz .LBB0_838
	s_and_b64 vcc, exec, s[0:1]
	s_cbranch_vccnz .LBB0_837
	v_lshlrev_b32_e32 v0, 7, v150
	v_lshl_add_u64 v[160:161], v[140:141], 0, v[0:1]
	v_mov_b32_e32 v156, v176
	v_mov_b32_e32 v157, v177
	v_mov_b32_e32 v158, v178
	v_mov_b32_e32 v159, v179
	v_mov_b32_e32 v160, v180
	v_mov_b32_e32 v161, v181
	v_mov_b32_e32 v162, v182
	v_mov_b32_e32 v163, v183
	v_pk_mul_f32 v[164:165], v[114:115], v[160:161]
	s_nop 0
	v_pk_fma_f32 v[164:165], v[128:129], v[156:157], v[164:165] neg_lo:[0,0,1] neg_hi:[0,0,1]
	v_pk_mul_f32 v[128:129], v[128:129], v[160:161]
	v_mul_f32_e32 v160, v120, v162
	v_pk_fma_f32 v[114:115], v[114:115], v[156:157], v[128:129]
	v_mul_f32_e32 v128, v120, v158
	v_mul_f32_e32 v156, v118, v162
	v_mul_f32_e32 v158, v118, v158
	v_mov_b32_e32 v118, v121
	v_mov_b32_e32 v162, v159
	v_pk_mul_f32 v[166:167], v[118:119], v[162:163]
	v_mov_b32_e32 v120, v119
	v_mov_b32_e32 v129, v166
	v_mov_b32_e32 v157, v167
	v_pk_mul_f32 v[118:119], v[120:121], v[162:163]
	v_pk_add_f32 v[156:157], v[128:129], v[156:157] neg_lo:[0,1] neg_hi:[0,1]
	v_mov_b32_e32 v159, v118
	v_mov_b32_e32 v161, v119
	v_pk_add_f32 v[118:119], v[158:159], v[160:161]
	v_mov_b32_e32 v128, v164
	v_mov_b32_e32 v129, v165
	v_mov_b32_e32 v120, v156
	v_mov_b32_e32 v121, v157

; DI unsigned cvtpk(float lo, float hi) { unsigned r; asm volatile("v_cvt_pk_bf16_f32 %0, %1, %2" : "=v"(r) : "v"(lo), "v"(hi)); return r; }
; DI bf16_t f2bf(float f) { return (bf16_t)(cvtpk(f, 0.f) & 0xffffu); }
; DI void rope128(f32x4& v0, f32x4& v1, const float* ropeA, int pos, int fq) {
;   const f32x4 cs = *(const f32x4*)(ropeA + pos * 32 + 4 * fq), sn = *(const f32x4*)(ropeA + pos * 32 + 16 + 4 * fq);
; #pragma unroll
;   for (int j = 0; j < 4; ++j) { const float x1 = v0[j], x2 = v1[j]; v0[j] = x1 * cs[j] - x2 * sn[j]; v1[j] = x2 * cs[j] + x1 * sn[j]; }
; }
; DI void store_vt(bf16_t* base  , int d0, int pos, const f32x4& v) {
; #pragma unroll
;   for (int j = 0; j < 4; ++j) base[(size_t)(d0 + j) * SL + pos] = f2bf(v[j]);
;   DI void operator()(const AccT& acc, const Unit& u, int wr, int wc, int fr, int fq) const {
;     ...
;           const float s = srow[row];
;           f32x4 v0 = acc[ai][bj][m][0] * s, v1 = acc[ai][bj][m][1] * s;
;           const int cin = wc * 32 + 4 * fq;
;           if (cb < 8) { if (wc == 0) rope128(v0, v1, ropeA, pos, fq);
;             bf16_t* dp = ak + (size_t)row * 1024 + cb * 128 + cin;
;             *(u32x2*)dp = (u32x2){cvtpk(v0[0], v0[1]), cvtpk(v0[2], v0[3])}; *(u32x2*)(dp + 16) = (u32x2){cvtpk(v1[0], v1[1]), cvtpk(v1[2], v1[3])}; }
;           else { bf16_t* base = avT + (size_t)((b * 8 + (cb - 8)) * 128) * SL; store_vt(base, cin, pos, v0); store_vt(base, cin + 16, pos, v1); }
.LBB0_838:
	s_movk_i32 s22, 0xfef
	v_or_b32_e32 v114, 32, v146
	v_bitop3_b32 v128, v146, s22, 32 bitop3:0xc8
	v_readlane_b32 s22, v250, 56
	v_ashrrev_i32_e32 v115, 31, v114
	v_readlane_b32 s23, v250, 57
	s_and_b64 vcc, exec, s[4:5]
	s_nop 0
	v_lshl_add_u64 v[118:119], v[114:115], 2, s[22:23]
	v_mov_b32_e32 v0, v219
	s_mov_b64 s[22:23], -1
	v_pk_mul_f32 v[112:113], v[112:113], v[0:1] op_sel_hi:[1,0]
	v_pk_mul_f32 v[120:121], v[110:111], v[0:1] op_sel_hi:[1,0]
	v_pk_mul_f32 v[110:111], v[108:109], v[0:1] op_sel_hi:[1,0]
	v_pk_mul_f32 v[106:107], v[106:107], v[0:1] op_sel_hi:[1,0]
	v_or_b32_e32 v0, v128, v153
	v_lshlrev_b32_e32 v108, 1, v0
	s_cbranch_vccnz .LBB0_840
	v_readlane_b32 s22, v251, 0
	s_add_u32 s22, s22, s20
	v_readlane_b32 s23, v251, 1
	s_addc_u32 s23, s23, s21
	v_mov_b32_e32 v109, v1
	v_cvt_pk_bf16_f32 v0, v120, v1
	v_lshl_add_u64 v[156:157], s[22:23], 0, v[108:109]
	s_nop 1
	global_store_short v108, v0, s[22:23]
	s_movk_i32 s22, 0x2000
	v_add_co_u32_e32 v158, vcc, s22, v156
	v_cvt_pk_bf16_f32 v0, v121, v1
	s_movk_i32 s22, 0x6000
	s_nop 0
	v_addc_co_u32_e32 v159, vcc, 0, v157, vcc
	global_store_short v[158:159], v0, off
	v_add_co_u32_e32 v158, vcc, s82, v156
	v_cvt_pk_bf16_f32 v0, v112, v1
	s_nop 1
	v_addc_co_u32_e32 v159, vcc, 0, v157, vcc
	global_store_short v[158:159], v0, off
	v_add_co_u32_e32 v158, vcc, s22, v156
	s_mov_b32 s22, 0x20000
	s_nop 0
	v_addc_co_u32_e32 v159, vcc, 0, v157, vcc
	v_cvt_pk_bf16_f32 v0, v113, v1
	global_store_short v[158:159], v0, off
	v_add_co_u32_e32 v158, vcc, s22, v156
	s_mov_b32 s22, 0x22000
	s_nop 0
	v_addc_co_u32_e32 v159, vcc, 0, v157, vcc
	v_cvt_pk_bf16_f32 v0, v106, v1
	global_store_short v[158:159], v0, off
	v_add_co_u32_e32 v158, vcc, s22, v156
	v_cvt_pk_bf16_f32 v0, v107, v1
	s_mov_b64 s[22:23], 0
	s_nop 0
	v_addc_co_u32_e32 v159, vcc, 0, v157, vcc
	global_store_short v[158:159], v0, off
	v_add_co_u32_e32 v158, vcc, 0x24000, v156
	v_cvt_pk_bf16_f32 v0, v110, v1
	s_nop 1
	v_addc_co_u32_e32 v159, vcc, 0, v157, vcc
	v_add_co_u32_e32 v156, vcc, 0x26000, v156
	global_store_short v[158:159], v0, off
	s_nop 0
	v_addc_co_u32_e32 v157, vcc, 0, v157, vcc
	v_cvt_pk_bf16_f32 v0, v111, v1
	global_store_short v[156:157], v0, off
.LBB0_840:
	s_andn2_b64 vcc, exec, s[22:23]
	s_cbranch_vccnz .LBB0_844
	s_and_b64 vcc, exec, s[0:1]
	s_cbranch_vccnz .LBB0_843
	v_lshlrev_b32_e32 v0, 7, v128
	v_lshl_add_u64 v[160:161], v[140:141], 0, v[0:1]
	v_mov_b32_e32 v156, v184
	v_mov_b32_e32 v157, v185
	v_mov_b32_e32 v158, v186
	v_mov_b32_e32 v159, v187
	v_mov_b32_e32 v160, v188
	v_mov_b32_e32 v161, v189
	v_mov_b32_e32 v162, v190
	v_mov_b32_e32 v163, v191
	v_pk_mul_f32 v[164:165], v[106:107], v[160:161]
	s_nop 0
	v_pk_fma_f32 v[164:165], v[120:121], v[156:157], v[164:165] neg_lo:[0,0,1] neg_hi:[0,0,1]
	v_pk_mul_f32 v[120:121], v[120:121], v[160:161]
	v_mul_f32_e32 v160, v112, v162
	v_pk_fma_f32 v[106:107], v[106:107], v[156:157], v[120:121]
	v_mul_f32_e32 v120, v112, v158
	v_mul_f32_e32 v156, v110, v162
	v_mul_f32_e32 v158, v110, v158
	v_mov_b32_e32 v110, v113
	v_mov_b32_e32 v162, v159
	v_pk_mul_f32 v[166:167], v[110:111], v[162:163]
	v_mov_b32_e32 v112, v111
	v_mov_b32_e32 v121, v166
	v_mov_b32_e32 v157, v167
	v_pk_mul_f32 v[110:111], v[112:113], v[162:163]
	v_pk_add_f32 v[156:157], v[120:121], v[156:157] neg_lo:[0,1] neg_hi:[0,1]
	v_mov_b32_e32 v159, v110
	v_mov_b32_e32 v161, v111
	v_pk_add_f32 v[110:111], v[158:159], v[160:161]
	v_mov_b32_e32 v120, v164
	v_mov_b32_e32 v121, v165
	v_mov_b32_e32 v112, v156
	v_mov_b32_e32 v113, v157

; DI unsigned cvtpk(float lo, float hi) { unsigned r; asm volatile("v_cvt_pk_bf16_f32 %0, %1, %2" : "=v"(r) : "v"(lo), "v"(hi)); return r; }
; DI bf16_t f2bf(float f) { return (bf16_t)(cvtpk(f, 0.f) & 0xffffu); }
; DI void rope128(f32x4& v0, f32x4& v1, const float* ropeA, int pos, int fq) {
;   const f32x4 cs = *(const f32x4*)(ropeA + pos * 32 + 4 * fq), sn = *(const f32x4*)(ropeA + pos * 32 + 16 + 4 * fq);
; #pragma unroll
;   for (int j = 0; j < 4; ++j) { const float x1 = v0[j], x2 = v1[j]; v0[j] = x1 * cs[j] - x2 * sn[j]; v1[j] = x2 * cs[j] + x1 * sn[j]; }
; }
; DI void store_vt(bf16_t* base  , int d0, int pos, const f32x4& v) {
; #pragma unroll
;   for (int j = 0; j < 4; ++j) base[(size_t)(d0 + j) * SL + pos] = f2bf(v[j]);
;   DI void operator()(const AccT& acc, const Unit& u, int wr, int wc, int fr, int fq) const {
;     ...
;           const float s = srow[row];
;           f32x4 v0 = acc[ai][bj][m][0] * s, v1 = acc[ai][bj][m][1] * s;
;           const int cin = wc * 32 + 4 * fq;
;           if (cb < 8) { if (wc == 0) rope128(v0, v1, ropeA, pos, fq);
;             bf16_t* dp = ak + (size_t)row * 1024 + cb * 128 + cin;
;             *(u32x2*)dp = (u32x2){cvtpk(v0[0], v0[1]), cvtpk(v0[2], v0[3])}; *(u32x2*)(dp + 16) = (u32x2){cvtpk(v1[0], v1[1]), cvtpk(v1[2], v1[3])}; }
;           else { bf16_t* base = avT + (size_t)((b * 8 + (cb - 8)) * 128) * SL; store_vt(base, cin, pos, v0); store_vt(base, cin + 16, pos, v1); }
.LBB0_844:
	s_movk_i32 s22, 0xfff
	v_or_b32_e32 v106, 48, v146
	v_bitop3_b32 v120, v146, s22, 48 bitop3:0xc8
	v_readlane_b32 s22, v250, 56
	v_ashrrev_i32_e32 v107, 31, v106
	v_readlane_b32 s23, v250, 57
	s_and_b64 vcc, exec, s[4:5]
	s_nop 0
	v_lshl_add_u64 v[110:111], v[106:107], 2, s[22:23]
	v_mov_b32_e32 v0, v223
	s_mov_b64 s[22:23], -1
	v_pk_mul_f32 v[104:105], v[104:105], v[0:1] op_sel_hi:[1,0]
	v_pk_mul_f32 v[112:113], v[102:103], v[0:1] op_sel_hi:[1,0]
	v_pk_mul_f32 v[102:103], v[100:101], v[0:1] op_sel_hi:[1,0]
	v_pk_mul_f32 v[98:99], v[98:99], v[0:1] op_sel_hi:[1,0]
	v_or_b32_e32 v0, v120, v153
	v_lshlrev_b32_e32 v100, 1, v0
	s_cbranch_vccnz .LBB0_846
	v_readlane_b32 s22, v251, 0
	s_add_u32 s20, s22, s20
	v_readlane_b32 s22, v251, 1
	s_addc_u32 s21, s22, s21
	v_mov_b32_e32 v101, v1
	v_cvt_pk_bf16_f32 v0, v112, v1
	v_lshl_add_u64 v[156:157], s[20:21], 0, v[100:101]
	global_store_short v100, v0, s[20:21]
	s_movk_i32 s20, 0x2000
	v_add_co_u32_e32 v158, vcc, s20, v156
	v_cvt_pk_bf16_f32 v0, v113, v1
	s_movk_i32 s20, 0x6000
	s_nop 0
	v_addc_co_u32_e32 v159, vcc, 0, v157, vcc
	global_store_short v[158:159], v0, off
	v_add_co_u32_e32 v158, vcc, s82, v156
	v_cvt_pk_bf16_f32 v0, v104, v1
	s_mov_b64 s[22:23], 0
	s_nop 0
	v_addc_co_u32_e32 v159, vcc, 0, v157, vcc
	global_store_short v[158:159], v0, off
	v_add_co_u32_e32 v158, vcc, s20, v156
	s_mov_b32 s20, 0x20000
	s_nop 0
	v_addc_co_u32_e32 v159, vcc, 0, v157, vcc
	v_cvt_pk_bf16_f32 v0, v105, v1
	global_store_short v[158:159], v0, off
	v_add_co_u32_e32 v158, vcc, s20, v156
	s_mov_b32 s20, 0x22000
	s_nop 0
	v_addc_co_u32_e32 v159, vcc, 0, v157, vcc
	v_cvt_pk_bf16_f32 v0, v98, v1
	global_store_short v[158:159], v0, off
	v_add_co_u32_e32 v158, vcc, s20, v156
	v_cvt_pk_bf16_f32 v0, v99, v1
	s_nop 1
	v_addc_co_u32_e32 v159, vcc, 0, v157, vcc
	global_store_short v[158:159], v0, off
	v_add_co_u32_e32 v158, vcc, 0x24000, v156
	v_cvt_pk_bf16_f32 v0, v102, v1
	s_nop 1
	v_addc_co_u32_e32 v159, vcc, 0, v157, vcc
	v_add_co_u32_e32 v156, vcc, 0x26000, v156
	global_store_short v[158:159], v0, off
	s_nop 0
	v_addc_co_u32_e32 v157, vcc, 0, v157, vcc
	v_cvt_pk_bf16_f32 v0, v103, v1
	global_store_short v[156:157], v0, off
.LBB0_846:
	s_andn2_b64 vcc, exec, s[22:23]
	s_cbranch_vccnz .LBB0_850
	s_and_b64 vcc, exec, s[0:1]
	s_cbranch_vccnz .LBB0_849
	v_lshlrev_b32_e32 v0, 7, v120
	v_lshl_add_u64 v[160:161], v[140:141], 0, v[0:1]
	v_mov_b32_e32 v156, v192
	v_mov_b32_e32 v157, v193
	v_mov_b32_e32 v158, v194
	v_mov_b32_e32 v159, v195
	v_mov_b32_e32 v160, v196
	v_mov_b32_e32 v161, v197
	v_mov_b32_e32 v162, v198
	v_mov_b32_e32 v163, v199
	v_pk_mul_f32 v[164:165], v[98:99], v[160:161]
	s_nop 0
	v_pk_fma_f32 v[164:165], v[112:113], v[156:157], v[164:165] neg_lo:[0,0,1] neg_hi:[0,0,1]
	v_pk_mul_f32 v[112:113], v[112:113], v[160:161]
	v_mul_f32_e32 v160, v104, v162
	v_pk_fma_f32 v[98:99], v[98:99], v[156:157], v[112:113]
	v_mul_f32_e32 v112, v104, v158
	v_mul_f32_e32 v156, v102, v162
	v_mul_f32_e32 v158, v102, v158
	v_mov_b32_e32 v102, v105
	v_mov_b32_e32 v162, v159
	v_pk_mul_f32 v[166:167], v[102:103], v[162:163]
	v_mov_b32_e32 v104, v103
	v_mov_b32_e32 v113, v166
	v_mov_b32_e32 v157, v167
	v_pk_mul_f32 v[102:103], v[104:105], v[162:163]
	v_pk_add_f32 v[156:157], v[112:113], v[156:157] neg_lo:[0,1] neg_hi:[0,1]
	v_mov_b32_e32 v159, v102
	v_mov_b32_e32 v161, v103
	v_pk_add_f32 v[102:103], v[158:159], v[160:161]
	v_mov_b32_e32 v112, v164
	v_mov_b32_e32 v113, v165
	v_mov_b32_e32 v104, v156
	v_mov_b32_e32 v105, v157

; DI unsigned cvtpk(float lo, float hi) { unsigned r; asm volatile("v_cvt_pk_bf16_f32 %0, %1, %2" : "=v"(r) : "v"(lo), "v"(hi)); return r; }
; DI bf16_t f2bf(float f) { return (bf16_t)(cvtpk(f, 0.f) & 0xffffu); }
; DI void rope128(f32x4& v0, f32x4& v1, const float* ropeA, int pos, int fq) {
;   const f32x4 cs = *(const f32x4*)(ropeA + pos * 32 + 4 * fq), sn = *(const f32x4*)(ropeA + pos * 32 + 16 + 4 * fq);
; #pragma unroll
;   for (int j = 0; j < 4; ++j) { const float x1 = v0[j], x2 = v1[j]; v0[j] = x1 * cs[j] - x2 * sn[j]; v1[j] = x2 * cs[j] + x1 * sn[j]; }
; }
; DI void store_vt(bf16_t* base  , int d0, int pos, const f32x4& v) {
; #pragma unroll
;   for (int j = 0; j < 4; ++j) base[(size_t)(d0 + j) * SL + pos] = f2bf(v[j]);
;   DI void operator()(const AccT& acc, const Unit& u, int wr, int wc, int fr, int fq) const {
;     ...
;           const float s = srow[row];
;           f32x4 v0 = acc[ai][bj][m][0] * s, v1 = acc[ai][bj][m][1] * s;
;           const int cin = wc * 32 + 4 * fq;
;           if (cb < 8) { if (wc == 0) rope128(v0, v1, ropeA, pos, fq);
;             bf16_t* dp = ak + (size_t)row * 1024 + cb * 128 + cin;
;             *(u32x2*)dp = (u32x2){cvtpk(v0[0], v0[1]), cvtpk(v0[2], v0[3])}; *(u32x2*)(dp + 16) = (u32x2){cvtpk(v1[0], v1[1]), cvtpk(v1[2], v1[3])}; }
;           else { bf16_t* base = avT + (size_t)((b * 8 + (cb - 8)) * 128) * SL; store_vt(base, cin, pos, v0); store_vt(base, cin + 16, pos, v1); }
.LBB0_850:
	s_addk_i32 s42, 0x80
	v_or_b32_e32 v98, s42, v139
	v_readlane_b32 s22, v250, 56
	v_ashrrev_i32_e32 v99, 31, v98
	v_readlane_b32 s23, v250, 57
	v_mov_b32_e32 v0, 0xfcf
	v_bitop3_b32 v112, s42, v0, v139 bitop3:0xc8
	v_lshl_add_u64 v[102:103], v[98:99], 2, s[22:23]
	v_mov_b32_e32 v0, v228
	s_ashr_i32 s20, s42, 9
	s_and_b32 s24, s20, -8
	s_add_i32 s20, s24, s41
	s_lshl_b32 s20, s20, 7
	s_ashr_i32 s21, s20, 31
	s_lshl_b64 s[20:21], s[20:21], 13
	s_mov_b64 s[22:23], -1
	s_and_b64 vcc, exec, s[4:5]
	v_pk_mul_f32 v[96:97], v[96:97], v[0:1] op_sel_hi:[1,0]
	v_pk_mul_f32 v[104:105], v[94:95], v[0:1] op_sel_hi:[1,0]
	v_pk_mul_f32 v[94:95], v[92:93], v[0:1] op_sel_hi:[1,0]
	v_pk_mul_f32 v[90:91], v[90:91], v[0:1] op_sel_hi:[1,0]
	v_or_b32_e32 v0, v112, v153
	v_lshlrev_b32_e32 v92, 1, v0
	s_cbranch_vccnz .LBB0_852
	v_readlane_b32 s22, v251, 0
	s_add_u32 s22, s22, s20
	v_readlane_b32 s23, v251, 1
	s_addc_u32 s23, s23, s21
	v_mov_b32_e32 v93, v1
	v_cvt_pk_bf16_f32 v0, v104, v1
	v_lshl_add_u64 v[156:157], s[22:23], 0, v[92:93]
	s_nop 1
	global_store_short v92, v0, s[22:23]
	s_movk_i32 s22, 0x2000
	v_add_co_u32_e32 v158, vcc, s22, v156
	v_cvt_pk_bf16_f32 v0, v105, v1
	s_movk_i32 s22, 0x6000
	s_nop 0
	v_addc_co_u32_e32 v159, vcc, 0, v157, vcc
	global_store_short v[158:159], v0, off
	v_add_co_u32_e32 v158, vcc, s82, v156
	v_cvt_pk_bf16_f32 v0, v96, v1
	s_nop 1
	v_addc_co_u32_e32 v159, vcc, 0, v157, vcc
	global_store_short v[158:159], v0, off
	v_add_co_u32_e32 v158, vcc, s22, v156
	s_mov_b32 s22, 0x20000
	s_nop 0
	v_addc_co_u32_e32 v159, vcc, 0, v157, vcc
	v_cvt_pk_bf16_f32 v0, v97, v1
	global_store_short v[158:159], v0, off
	v_add_co_u32_e32 v158, vcc, s22, v156
	s_mov_b32 s22, 0x22000
	s_nop 0
	v_addc_co_u32_e32 v159, vcc, 0, v157, vcc
	v_cvt_pk_bf16_f32 v0, v90, v1
	global_store_short v[158:159], v0, off
	v_add_co_u32_e32 v158, vcc, s22, v156
	v_cvt_pk_bf16_f32 v0, v91, v1
	s_mov_b64 s[22:23], 0
	s_nop 0
	v_addc_co_u32_e32 v159, vcc, 0, v157, vcc
	global_store_short v[158:159], v0, off
	v_add_co_u32_e32 v158, vcc, 0x24000, v156
	v_cvt_pk_bf16_f32 v0, v94, v1
	s_nop 1
	v_addc_co_u32_e32 v159, vcc, 0, v157, vcc
	v_add_co_u32_e32 v156, vcc, 0x26000, v156
	global_store_short v[158:159], v0, off
	s_nop 0
	v_addc_co_u32_e32 v157, vcc, 0, v157, vcc
	v_cvt_pk_bf16_f32 v0, v95, v1
	global_store_short v[156:157], v0, off
.LBB0_852:
	s_andn2_b64 vcc, exec, s[22:23]
	s_cbranch_vccnz .LBB0_856
	s_and_b64 vcc, exec, s[0:1]
	s_cbranch_vccnz .LBB0_855
	v_lshlrev_b32_e32 v0, 7, v112
	v_lshl_add_u64 v[160:161], v[140:141], 0, v[0:1]
	v_mov_b32_e32 v156, v200
	v_mov_b32_e32 v157, v201
	v_mov_b32_e32 v158, v202
	v_mov_b32_e32 v159, v203
	v_mov_b32_e32 v160, v204
	v_mov_b32_e32 v161, v205
	v_mov_b32_e32 v162, v206
	v_mov_b32_e32 v163, v207
	v_pk_mul_f32 v[164:165], v[90:91], v[160:161]
	s_nop 0
	v_pk_fma_f32 v[164:165], v[104:105], v[156:157], v[164:165] neg_lo:[0,0,1] neg_hi:[0,0,1]
	v_pk_mul_f32 v[104:105], v[104:105], v[160:161]
	v_mul_f32_e32 v160, v96, v162
	v_pk_fma_f32 v[90:91], v[90:91], v[156:157], v[104:105]
	v_mul_f32_e32 v104, v96, v158
	v_mul_f32_e32 v156, v94, v162
	v_mul_f32_e32 v158, v94, v158
	v_mov_b32_e32 v94, v97
	v_mov_b32_e32 v162, v159
	v_pk_mul_f32 v[166:167], v[94:95], v[162:163]
	v_mov_b32_e32 v96, v95
	v_mov_b32_e32 v105, v166
	v_mov_b32_e32 v157, v167
	v_pk_mul_f32 v[94:95], v[96:97], v[162:163]
	v_pk_add_f32 v[156:157], v[104:105], v[156:157] neg_lo:[0,1] neg_hi:[0,1]
	v_mov_b32_e32 v159, v94
	v_mov_b32_e32 v161, v95
	v_pk_add_f32 v[94:95], v[158:159], v[160:161]
	v_mov_b32_e32 v104, v164
	v_mov_b32_e32 v105, v165
	v_mov_b32_e32 v96, v156
	v_mov_b32_e32 v97, v157

; DI unsigned cvtpk(float lo, float hi) { unsigned r; asm volatile("v_cvt_pk_bf16_f32 %0, %1, %2" : "=v"(r) : "v"(lo), "v"(hi)); return r; }
; DI bf16_t f2bf(float f) { return (bf16_t)(cvtpk(f, 0.f) & 0xffffu); }
; DI void rope128(f32x4& v0, f32x4& v1, const float* ropeA, int pos, int fq) {
;   const f32x4 cs = *(const f32x4*)(ropeA + pos * 32 + 4 * fq), sn = *(const f32x4*)(ropeA + pos * 32 + 16 + 4 * fq);
; #pragma unroll
;   for (int j = 0; j < 4; ++j) { const float x1 = v0[j], x2 = v1[j]; v0[j] = x1 * cs[j] - x2 * sn[j]; v1[j] = x2 * cs[j] + x1 * sn[j]; }
; }
; DI void store_vt(bf16_t* base  , int d0, int pos, const f32x4& v) {
; #pragma unroll
;   for (int j = 0; j < 4; ++j) base[(size_t)(d0 + j) * SL + pos] = f2bf(v[j]);
;   DI void operator()(const AccT& acc, const Unit& u, int wr, int wc, int fr, int fq) const {
;     ...
;           const float s = srow[row];
;           f32x4 v0 = acc[ai][bj][m][0] * s, v1 = acc[ai][bj][m][1] * s;
;           const int cin = wc * 32 + 4 * fq;
;           if (cb < 8) { if (wc == 0) rope128(v0, v1, ropeA, pos, fq);
;             bf16_t* dp = ak + (size_t)row * 1024 + cb * 128 + cin;
;             *(u32x2*)dp = (u32x2){cvtpk(v0[0], v0[1]), cvtpk(v0[2], v0[3])}; *(u32x2*)(dp + 16) = (u32x2){cvtpk(v1[0], v1[1]), cvtpk(v1[2], v1[3])}; }
;           else { bf16_t* base = avT + (size_t)((b * 8 + (cb - 8)) * 128) * SL; store_vt(base, cin, pos, v0); store_vt(base, cin + 16, pos, v1); }
.LBB0_856:
	s_movk_i32 s22, 0xfdf
	v_or_b32_e32 v90, 16, v98
	v_bitop3_b32 v104, v98, s22, 16 bitop3:0xc8
	v_readlane_b32 s22, v250, 56
	v_ashrrev_i32_e32 v91, 31, v90
	v_readlane_b32 s23, v250, 57
	s_and_b64 vcc, exec, s[4:5]
	s_nop 0
	v_lshl_add_u64 v[94:95], v[90:91], 2, s[22:23]
	v_mov_b32_e32 v0, v231
	s_mov_b64 s[22:23], -1
	v_pk_mul_f32 v[88:89], v[88:89], v[0:1] op_sel_hi:[1,0]
	v_pk_mul_f32 v[96:97], v[86:87], v[0:1] op_sel_hi:[1,0]
	v_pk_mul_f32 v[86:87], v[84:85], v[0:1] op_sel_hi:[1,0]
	v_pk_mul_f32 v[82:83], v[82:83], v[0:1] op_sel_hi:[1,0]
	v_or_b32_e32 v0, v104, v153
	v_lshlrev_b32_e32 v84, 1, v0
	s_cbranch_vccnz .LBB0_858
	v_readlane_b32 s22, v251, 0
	s_add_u32 s22, s22, s20
	v_readlane_b32 s23, v251, 1
	s_addc_u32 s23, s23, s21
	v_mov_b32_e32 v85, v1
	v_cvt_pk_bf16_f32 v0, v96, v1
	v_lshl_add_u64 v[156:157], s[22:23], 0, v[84:85]
	s_nop 1
	global_store_short v84, v0, s[22:23]
	s_movk_i32 s22, 0x2000
	v_add_co_u32_e32 v158, vcc, s22, v156
	v_cvt_pk_bf16_f32 v0, v97, v1
	s_movk_i32 s22, 0x6000
	s_nop 0
	v_addc_co_u32_e32 v159, vcc, 0, v157, vcc
	global_store_short v[158:159], v0, off
	v_add_co_u32_e32 v158, vcc, s82, v156
	v_cvt_pk_bf16_f32 v0, v88, v1
	s_nop 1
	v_addc_co_u32_e32 v159, vcc, 0, v157, vcc
	global_store_short v[158:159], v0, off
	v_add_co_u32_e32 v158, vcc, s22, v156
	s_mov_b32 s22, 0x20000
	s_nop 0
	v_addc_co_u32_e32 v159, vcc, 0, v157, vcc
	v_cvt_pk_bf16_f32 v0, v89, v1
	global_store_short v[158:159], v0, off
	v_add_co_u32_e32 v158, vcc, s22, v156
	s_mov_b32 s22, 0x22000
	s_nop 0
	v_addc_co_u32_e32 v159, vcc, 0, v157, vcc
	v_cvt_pk_bf16_f32 v0, v82, v1
	global_store_short v[158:159], v0, off
	v_add_co_u32_e32 v158, vcc, s22, v156
	v_cvt_pk_bf16_f32 v0, v83, v1
	s_mov_b64 s[22:23], 0
	s_nop 0
	v_addc_co_u32_e32 v159, vcc, 0, v157, vcc
	global_store_short v[158:159], v0, off
	v_add_co_u32_e32 v158, vcc, 0x24000, v156
	v_cvt_pk_bf16_f32 v0, v86, v1
	s_nop 1
	v_addc_co_u32_e32 v159, vcc, 0, v157, vcc
	v_add_co_u32_e32 v156, vcc, 0x26000, v156
	global_store_short v[158:159], v0, off
	s_nop 0
	v_addc_co_u32_e32 v157, vcc, 0, v157, vcc
	v_cvt_pk_bf16_f32 v0, v87, v1
	global_store_short v[156:157], v0, off
.LBB0_858:
	s_andn2_b64 vcc, exec, s[22:23]
	s_cbranch_vccnz .LBB0_862
	s_and_b64 vcc, exec, s[0:1]
	s_cbranch_vccnz .LBB0_861
	v_lshlrev_b32_e32 v0, 7, v104
	v_lshl_add_u64 v[160:161], v[140:141], 0, v[0:1]
	v_mov_b32_e32 v156, v208
	v_mov_b32_e32 v157, v209
	v_mov_b32_e32 v158, v210
	v_mov_b32_e32 v159, v211
	v_mov_b32_e32 v160, v214
	v_mov_b32_e32 v161, v215
	v_mov_b32_e32 v162, v216
	v_mov_b32_e32 v163, v217
	v_pk_mul_f32 v[164:165], v[82:83], v[160:161]
	s_nop 0
	v_pk_fma_f32 v[164:165], v[96:97], v[156:157], v[164:165] neg_lo:[0,0,1] neg_hi:[0,0,1]
	v_pk_mul_f32 v[96:97], v[96:97], v[160:161]
	v_mul_f32_e32 v160, v88, v162
	v_pk_fma_f32 v[82:83], v[82:83], v[156:157], v[96:97]
	v_mul_f32_e32 v96, v88, v158
	v_mul_f32_e32 v156, v86, v162
	v_mul_f32_e32 v158, v86, v158
	v_mov_b32_e32 v86, v89
	v_mov_b32_e32 v162, v159
	v_pk_mul_f32 v[166:167], v[86:87], v[162:163]
	v_mov_b32_e32 v88, v87
	v_mov_b32_e32 v97, v166
	v_mov_b32_e32 v157, v167
	v_pk_mul_f32 v[86:87], v[88:89], v[162:163]
	v_pk_add_f32 v[156:157], v[96:97], v[156:157] neg_lo:[0,1] neg_hi:[0,1]
	v_mov_b32_e32 v159, v86
	v_mov_b32_e32 v161, v87
	v_pk_add_f32 v[86:87], v[158:159], v[160:161]
	v_mov_b32_e32 v96, v164
	v_mov_b32_e32 v97, v165
	v_mov_b32_e32 v88, v156
	v_mov_b32_e32 v89, v157

; DI unsigned cvtpk(float lo, float hi) { unsigned r; asm volatile("v_cvt_pk_bf16_f32 %0, %1, %2" : "=v"(r) : "v"(lo), "v"(hi)); return r; }
; DI bf16_t f2bf(float f) { return (bf16_t)(cvtpk(f, 0.f) & 0xffffu); }
; DI void rope128(f32x4& v0, f32x4& v1, const float* ropeA, int pos, int fq) {
;   const f32x4 cs = *(const f32x4*)(ropeA + pos * 32 + 4 * fq), sn = *(const f32x4*)(ropeA + pos * 32 + 16 + 4 * fq);
; #pragma unroll
;   for (int j = 0; j < 4; ++j) { const float x1 = v0[j], x2 = v1[j]; v0[j] = x1 * cs[j] - x2 * sn[j]; v1[j] = x2 * cs[j] + x1 * sn[j]; }
; }
; DI void store_vt(bf16_t* base  , int d0, int pos, const f32x4& v) {
; #pragma unroll
;   for (int j = 0; j < 4; ++j) base[(size_t)(d0 + j) * SL + pos] = f2bf(v[j]);
;   DI void operator()(const AccT& acc, const Unit& u, int wr, int wc, int fr, int fq) const {
;     ...
;           const float s = srow[row];
;           f32x4 v0 = acc[ai][bj][m][0] * s, v1 = acc[ai][bj][m][1] * s;
;           const int cin = wc * 32 + 4 * fq;
;           if (cb < 8) { if (wc == 0) rope128(v0, v1, ropeA, pos, fq);
;             bf16_t* dp = ak + (size_t)row * 1024 + cb * 128 + cin;
;             *(u32x2*)dp = (u32x2){cvtpk(v0[0], v0[1]), cvtpk(v0[2], v0[3])}; *(u32x2*)(dp + 16) = (u32x2){cvtpk(v1[0], v1[1]), cvtpk(v1[2], v1[3])}; }
;           else { bf16_t* base = avT + (size_t)((b * 8 + (cb - 8)) * 128) * SL; store_vt(base, cin, pos, v0); store_vt(base, cin + 16, pos, v1); }
.LBB0_862:
	s_movk_i32 s22, 0xfef
	v_or_b32_e32 v82, 32, v98
	v_bitop3_b32 v96, v98, s22, 32 bitop3:0xc8
	v_readlane_b32 s22, v250, 56
	v_ashrrev_i32_e32 v83, 31, v82
	v_readlane_b32 s23, v250, 57
	s_and_b64 vcc, exec, s[4:5]
	s_nop 0
	v_lshl_add_u64 v[86:87], v[82:83], 2, s[22:23]
	v_mov_b32_e32 v0, v244
	s_mov_b64 s[22:23], -1
	v_pk_mul_f32 v[80:81], v[80:81], v[0:1] op_sel_hi:[1,0]
	v_pk_mul_f32 v[88:89], v[78:79], v[0:1] op_sel_hi:[1,0]
	v_pk_mul_f32 v[78:79], v[76:77], v[0:1] op_sel_hi:[1,0]
	v_pk_mul_f32 v[74:75], v[74:75], v[0:1] op_sel_hi:[1,0]
	v_or_b32_e32 v0, v96, v153
	v_lshlrev_b32_e32 v76, 1, v0
	s_cbranch_vccnz .LBB0_864
	v_readlane_b32 s22, v251, 0
	s_add_u32 s22, s22, s20
	v_readlane_b32 s23, v251, 1
	s_addc_u32 s23, s23, s21
	v_mov_b32_e32 v77, v1
	v_cvt_pk_bf16_f32 v0, v88, v1
	v_lshl_add_u64 v[156:157], s[22:23], 0, v[76:77]
	s_nop 1
	global_store_short v76, v0, s[22:23]
	s_movk_i32 s22, 0x2000
	v_add_co_u32_e32 v158, vcc, s22, v156
	v_cvt_pk_bf16_f32 v0, v89, v1
	s_movk_i32 s22, 0x6000
	s_nop 0
	v_addc_co_u32_e32 v159, vcc, 0, v157, vcc
	global_store_short v[158:159], v0, off
	v_add_co_u32_e32 v158, vcc, s82, v156
	v_cvt_pk_bf16_f32 v0, v80, v1
	s_nop 1
	v_addc_co_u32_e32 v159, vcc, 0, v157, vcc
	global_store_short v[158:159], v0, off
	v_add_co_u32_e32 v158, vcc, s22, v156
	s_mov_b32 s22, 0x20000
	s_nop 0
	v_addc_co_u32_e32 v159, vcc, 0, v157, vcc
	v_cvt_pk_bf16_f32 v0, v81, v1
	global_store_short v[158:159], v0, off
	v_add_co_u32_e32 v158, vcc, s22, v156
	s_mov_b32 s22, 0x22000
	s_nop 0
	v_addc_co_u32_e32 v159, vcc, 0, v157, vcc
	v_cvt_pk_bf16_f32 v0, v74, v1
	global_store_short v[158:159], v0, off
	v_add_co_u32_e32 v158, vcc, s22, v156
	v_cvt_pk_bf16_f32 v0, v75, v1
	s_mov_b64 s[22:23], 0
	s_nop 0
	v_addc_co_u32_e32 v159, vcc, 0, v157, vcc
	global_store_short v[158:159], v0, off
	v_add_co_u32_e32 v158, vcc, 0x24000, v156
	v_cvt_pk_bf16_f32 v0, v78, v1
	s_nop 1
	v_addc_co_u32_e32 v159, vcc, 0, v157, vcc
	v_add_co_u32_e32 v156, vcc, 0x26000, v156
	global_store_short v[158:159], v0, off
	s_nop 0
	v_addc_co_u32_e32 v157, vcc, 0, v157, vcc
	v_cvt_pk_bf16_f32 v0, v79, v1
	global_store_short v[156:157], v0, off
.LBB0_864:
	s_andn2_b64 vcc, exec, s[22:23]
	s_cbranch_vccnz .LBB0_868
	s_and_b64 vcc, exec, s[0:1]
	s_cbranch_vccnz .LBB0_867
	v_lshlrev_b32_e32 v0, 7, v96
	v_lshl_add_u64 v[160:161], v[140:141], 0, v[0:1]
	v_mov_b32_e32 v156, v224
	v_mov_b32_e32 v157, v225
	v_mov_b32_e32 v158, v226
	v_mov_b32_e32 v159, v227
	v_mov_b32_e32 v160, v232
	v_mov_b32_e32 v161, v233
	v_mov_b32_e32 v162, v234
	v_mov_b32_e32 v163, v235
	v_pk_mul_f32 v[164:165], v[74:75], v[160:161]
	s_nop 0
	v_pk_fma_f32 v[164:165], v[88:89], v[156:157], v[164:165] neg_lo:[0,0,1] neg_hi:[0,0,1]
	v_pk_mul_f32 v[88:89], v[88:89], v[160:161]
	v_mul_f32_e32 v160, v80, v162
	v_pk_fma_f32 v[74:75], v[74:75], v[156:157], v[88:89]
	v_mul_f32_e32 v88, v80, v158
	v_mul_f32_e32 v156, v78, v162
	v_mul_f32_e32 v158, v78, v158
	v_mov_b32_e32 v78, v81
	v_mov_b32_e32 v162, v159
	v_pk_mul_f32 v[166:167], v[78:79], v[162:163]
	v_mov_b32_e32 v80, v79
	v_mov_b32_e32 v89, v166
	v_mov_b32_e32 v157, v167
	v_pk_mul_f32 v[78:79], v[80:81], v[162:163]
	v_pk_add_f32 v[156:157], v[88:89], v[156:157] neg_lo:[0,1] neg_hi:[0,1]
	v_mov_b32_e32 v159, v78
	v_mov_b32_e32 v161, v79
	v_pk_add_f32 v[78:79], v[158:159], v[160:161]
	v_mov_b32_e32 v88, v164
	v_mov_b32_e32 v89, v165
	v_mov_b32_e32 v80, v156
	v_mov_b32_e32 v81, v157

; DI unsigned cvtpk(float lo, float hi) { unsigned r; asm volatile("v_cvt_pk_bf16_f32 %0, %1, %2" : "=v"(r) : "v"(lo), "v"(hi)); return r; }
; DI bf16_t f2bf(float f) { return (bf16_t)(cvtpk(f, 0.f) & 0xffffu); }
; DI void rope128(f32x4& v0, f32x4& v1, const float* ropeA, int pos, int fq) {
;   const f32x4 cs = *(const f32x4*)(ropeA + pos * 32 + 4 * fq), sn = *(const f32x4*)(ropeA + pos * 32 + 16 + 4 * fq);
; #pragma unroll
;   for (int j = 0; j < 4; ++j) { const float x1 = v0[j], x2 = v1[j]; v0[j] = x1 * cs[j] - x2 * sn[j]; v1[j] = x2 * cs[j] + x1 * sn[j]; }
; }
; DI void store_vt(bf16_t* base  , int d0, int pos, const f32x4& v) {
; #pragma unroll
;   for (int j = 0; j < 4; ++j) base[(size_t)(d0 + j) * SL + pos] = f2bf(v[j]);
;   DI void operator()(const AccT& acc, const Unit& u, int wr, int wc, int fr, int fq) const {
;     ...
;           const float s = srow[row];
;           f32x4 v0 = acc[ai][bj][m][0] * s, v1 = acc[ai][bj][m][1] * s;
;           const int cin = wc * 32 + 4 * fq;
;           if (cb < 8) { if (wc == 0) rope128(v0, v1, ropeA, pos, fq);
;             bf16_t* dp = ak + (size_t)row * 1024 + cb * 128 + cin;
;             *(u32x2*)dp = (u32x2){cvtpk(v0[0], v0[1]), cvtpk(v0[2], v0[3])}; *(u32x2*)(dp + 16) = (u32x2){cvtpk(v1[0], v1[1]), cvtpk(v1[2], v1[3])}; }
;           else { bf16_t* base = avT + (size_t)((b * 8 + (cb - 8)) * 128) * SL; store_vt(base, cin, pos, v0); store_vt(base, cin + 16, pos, v1); }
.LBB0_868:
	s_movk_i32 s22, 0xfff
	v_or_b32_e32 v74, 48, v98
	v_bitop3_b32 v88, v98, s22, 48 bitop3:0xc8
	v_readlane_b32 s22, v250, 56
	v_ashrrev_i32_e32 v75, 31, v74
	v_readlane_b32 s23, v250, 57
	s_and_b64 vcc, exec, s[4:5]
	s_nop 0
	v_lshl_add_u64 v[78:79], v[74:75], 2, s[22:23]
	v_mov_b32_e32 v0, v245
	s_mov_b64 s[22:23], -1
	v_pk_mul_f32 v[72:73], v[72:73], v[0:1] op_sel_hi:[1,0]
	v_pk_mul_f32 v[80:81], v[70:71], v[0:1] op_sel_hi:[1,0]
	v_pk_mul_f32 v[70:71], v[68:69], v[0:1] op_sel_hi:[1,0]
	v_pk_mul_f32 v[68:69], v[66:67], v[0:1] op_sel_hi:[1,0]
	v_or_b32_e32 v0, v88, v153
	v_lshlrev_b32_e32 v66, 1, v0
	s_cbranch_vccnz .LBB0_870
	v_readlane_b32 s4, v251, 0
	s_add_u32 s4, s4, s20
	v_readlane_b32 s5, v251, 1
	s_addc_u32 s5, s5, s21
	v_mov_b32_e32 v67, v1
	v_cvt_pk_bf16_f32 v0, v80, v1
	v_lshl_add_u64 v[156:157], s[4:5], 0, v[66:67]
	s_mov_b64 s[22:23], 0
	s_nop 0
	global_store_short v66, v0, s[4:5]
	s_movk_i32 s4, 0x2000
	v_add_co_u32_e32 v158, vcc, s4, v156
	v_cvt_pk_bf16_f32 v0, v81, v1
	s_movk_i32 s4, 0x6000
	s_nop 0
	v_addc_co_u32_e32 v159, vcc, 0, v157, vcc
	global_store_short v[158:159], v0, off
	v_add_co_u32_e32 v158, vcc, s82, v156
	v_cvt_pk_bf16_f32 v0, v72, v1
	s_nop 1
	v_addc_co_u32_e32 v159, vcc, 0, v157, vcc
	global_store_short v[158:159], v0, off
	v_add_co_u32_e32 v158, vcc, s4, v156
	s_mov_b32 s4, 0x20000
	s_nop 0
	v_addc_co_u32_e32 v159, vcc, 0, v157, vcc
	v_cvt_pk_bf16_f32 v0, v73, v1
	global_store_short v[158:159], v0, off
	v_add_co_u32_e32 v158, vcc, s4, v156
	s_mov_b32 s4, 0x22000
	s_nop 0
	v_addc_co_u32_e32 v159, vcc, 0, v157, vcc
	v_cvt_pk_bf16_f32 v0, v68, v1
	global_store_short v[158:159], v0, off
	v_add_co_u32_e32 v158, vcc, s4, v156
	v_cvt_pk_bf16_f32 v0, v69, v1
	s_nop 1
	v_addc_co_u32_e32 v159, vcc, 0, v157, vcc
	global_store_short v[158:159], v0, off
	v_add_co_u32_e32 v158, vcc, 0x24000, v156
	v_cvt_pk_bf16_f32 v0, v70, v1
	s_nop 1
	v_addc_co_u32_e32 v159, vcc, 0, v157, vcc
	v_add_co_u32_e32 v156, vcc, 0x26000, v156
	global_store_short v[158:159], v0, off
	s_nop 0
	v_addc_co_u32_e32 v157, vcc, 0, v157, vcc
	v_cvt_pk_bf16_f32 v0, v71, v1
	global_store_short v[156:157], v0, off
.LBB0_870:
	s_andn2_b64 vcc, exec, s[22:23]
	s_cbranch_vccnz .LBB0_874
	s_and_b64 vcc, exec, s[0:1]
	s_cbranch_vccnz .LBB0_873
	v_lshlrev_b32_e32 v0, 7, v88
	v_lshl_add_u64 v[160:161], v[140:141], 0, v[0:1]
	v_mov_b32_e32 v156, v236
	v_mov_b32_e32 v157, v237
	v_mov_b32_e32 v158, v238
	v_mov_b32_e32 v159, v239
	v_mov_b32_e32 v160, v240
	v_mov_b32_e32 v161, v241
	v_mov_b32_e32 v162, v242
	v_mov_b32_e32 v163, v243
	v_pk_mul_f32 v[164:165], v[68:69], v[160:161]
	s_nop 0
	v_pk_fma_f32 v[164:165], v[80:81], v[156:157], v[164:165] neg_lo:[0,0,1] neg_hi:[0,0,1]
	v_pk_mul_f32 v[80:81], v[80:81], v[160:161]
	v_mul_f32_e32 v160, v72, v162
	v_pk_fma_f32 v[68:69], v[68:69], v[156:157], v[80:81]
	v_mul_f32_e32 v80, v72, v158
	v_mul_f32_e32 v156, v70, v162
	v_mul_f32_e32 v158, v70, v158
	v_mov_b32_e32 v70, v73
	v_mov_b32_e32 v162, v159
	v_pk_mul_f32 v[166:167], v[70:71], v[162:163]
	v_mov_b32_e32 v72, v71
	v_mov_b32_e32 v81, v166
	v_mov_b32_e32 v157, v167
	v_pk_mul_f32 v[70:71], v[72:73], v[162:163]
	v_pk_add_f32 v[156:157], v[80:81], v[156:157] neg_lo:[0,1] neg_hi:[0,1]
	v_mov_b32_e32 v159, v70
	v_mov_b32_e32 v161, v71
	v_pk_add_f32 v[70:71], v[158:159], v[160:161]
	v_mov_b32_e32 v80, v164
	v_mov_b32_e32 v81, v165
	v_mov_b32_e32 v72, v156
	v_mov_b32_e32 v73, v157

; DI unsigned cvtpk(float lo, float hi) { unsigned r; asm volatile("v_cvt_pk_bf16_f32 %0, %1, %2" : "=v"(r) : "v"(lo), "v"(hi)); return r; }
; DI bf16_t f2bf(float f) { return (bf16_t)(cvtpk(f, 0.f) & 0xffffu); }
; DI void rope128(f32x4& v0, f32x4& v1, const float* ropeA, int pos, int fq) {
;   const f32x4 cs = *(const f32x4*)(ropeA + pos * 32 + 4 * fq), sn = *(const f32x4*)(ropeA + pos * 32 + 16 + 4 * fq);
; #pragma unroll
;   for (int j = 0; j < 4; ++j) { const float x1 = v0[j], x2 = v1[j]; v0[j] = x1 * cs[j] - x2 * sn[j]; v1[j] = x2 * cs[j] + x1 * sn[j]; }
; }
; DI void store_vt(bf16_t* base  , int d0, int pos, const f32x4& v) {
; #pragma unroll
;   for (int j = 0; j < 4; ++j) base[(size_t)(d0 + j) * SL + pos] = f2bf(v[j]);
;   DI void operator()(const AccT& acc, const Unit& u, int wr, int wc, int fr, int fq) const {
;     ...
;           const float s = srow[row];
;           f32x4 v0 = acc[ai][bj][m][0] * s, v1 = acc[ai][bj][m][1] * s;
;           const int cin = wc * 32 + 4 * fq;
;           if (cb < 8) { if (wc == 0) rope128(v0, v1, ropeA, pos, fq);
;             bf16_t* dp = ak + (size_t)row * 1024 + cb * 128 + cin;
;             *(u32x2*)dp = (u32x2){cvtpk(v0[0], v0[1]), cvtpk(v0[2], v0[3])}; *(u32x2*)(dp + 16) = (u32x2){cvtpk(v1[0], v1[1]), cvtpk(v1[2], v1[3])}; }
;           else { bf16_t* base = avT + (size_t)((b * 8 + (cb - 8)) * 128) * SL; store_vt(base, cin, pos, v0); store_vt(base, cin + 16, pos, v1); }
.LBB0_874:
	v_mov_b32_e32 v0, v213
	s_or_b32 s18, s13, 1
	s_cmp_gt_i32 s18, 7
	s_cselect_b64 s[22:23], -1, 0
	s_add_i32 s13, s13, -7
	s_add_i32 s40, s40, s13
	s_lshl_b32 s4, s40, 7
	s_ashr_i32 s5, s4, 31
	s_lshl_b64 s[20:21], s[4:5], 13
	s_cmp_lt_i32 s18, 8
	s_mov_b64 s[4:5], -1
	v_pk_mul_f32 v[64:65], v[64:65], v[0:1] op_sel_hi:[1,0]
	v_pk_mul_f32 v[62:63], v[62:63], v[0:1] op_sel_hi:[1,0]
	v_pk_mul_f32 v[60:61], v[60:61], v[0:1] op_sel_hi:[1,0]
	v_pk_mul_f32 v[58:59], v[58:59], v[0:1] op_sel_hi:[1,0]
	s_cbranch_scc1 .LBB0_876
	v_readlane_b32 s4, v251, 0
	s_add_u32 s4, s4, s20
	v_readlane_b32 s5, v251, 1
	s_addc_u32 s5, s5, s21
	v_mov_b32_e32 v125, v1
	v_cvt_pk_bf16_f32 v0, v62, v1
	v_lshl_add_u64 v[68:69], s[4:5], 0, v[124:125]
	s_nop 1
	global_store_short v124, v0, s[4:5]
	s_movk_i32 s4, 0x2000
	v_add_co_u32_e32 v70, vcc, s4, v68
	v_cvt_pk_bf16_f32 v0, v63, v1
	s_movk_i32 s4, 0x6000
	s_nop 0
	v_addc_co_u32_e32 v71, vcc, 0, v69, vcc
	global_store_short v[70:71], v0, off
	v_add_co_u32_e32 v70, vcc, s82, v68
	v_cvt_pk_bf16_f32 v0, v64, v1
	s_nop 1
	v_addc_co_u32_e32 v71, vcc, 0, v69, vcc
	global_store_short v[70:71], v0, off
	v_add_co_u32_e32 v70, vcc, s4, v68
	s_mov_b32 s4, 0x20000
	s_nop 0
	v_addc_co_u32_e32 v71, vcc, 0, v69, vcc
	v_cvt_pk_bf16_f32 v0, v65, v1
	global_store_short v[70:71], v0, off
	v_add_co_u32_e32 v70, vcc, s4, v68
	s_mov_b32 s4, 0x22000
	s_nop 0
	v_addc_co_u32_e32 v71, vcc, 0, v69, vcc
	v_cvt_pk_bf16_f32 v0, v58, v1
	global_store_short v[70:71], v0, off
	v_add_co_u32_e32 v70, vcc, s4, v68
	v_cvt_pk_bf16_f32 v0, v59, v1
	s_mov_b64 s[4:5], 0
	s_nop 0
	v_addc_co_u32_e32 v71, vcc, 0, v69, vcc
	global_store_short v[70:71], v0, off
	v_add_co_u32_e32 v70, vcc, 0x24000, v68
	v_cvt_pk_bf16_f32 v0, v60, v1
	s_nop 1
	v_addc_co_u32_e32 v71, vcc, 0, v69, vcc
	v_add_co_u32_e32 v68, vcc, 0x26000, v68
	global_store_short v[70:71], v0, off
	s_nop 0
	v_addc_co_u32_e32 v69, vcc, 0, v69, vcc
	v_cvt_pk_bf16_f32 v0, v61, v1
	global_store_short v[68:69], v0, off
.LBB0_876:
	s_lshl_b32 s18, s18, 7
	s_andn2_b64 vcc, exec, s[4:5]
	s_ashr_i32 s19, s18, 31
	s_cbranch_vccnz .LBB0_880
	s_and_b64 vcc, exec, s[0:1]
	s_cbranch_vccnz .LBB0_879
	v_lshlrev_b32_e32 v0, 7, v155
	v_lshl_add_u64 v[72:73], v[140:141], 0, v[0:1]
	v_mov_b32_e32 v68, v168
	v_mov_b32_e32 v69, v169
	v_mov_b32_e32 v70, v170
	v_mov_b32_e32 v71, v171
	v_mov_b32_e32 v156, v172
	v_mov_b32_e32 v157, v173
	v_mov_b32_e32 v158, v174
	v_mov_b32_e32 v159, v175
	v_pk_mul_f32 v[72:73], v[58:59], v[156:157]
	s_nop 0
	v_pk_fma_f32 v[72:73], v[62:63], v[68:69], v[72:73] neg_lo:[0,0,1] neg_hi:[0,0,1]
	v_pk_mul_f32 v[62:63], v[62:63], v[156:157]
	v_mul_f32_e32 v80, v64, v158
	v_pk_fma_f32 v[58:59], v[58:59], v[68:69], v[62:63]
	v_mul_f32_e32 v62, v64, v70
	v_mul_f32_e32 v68, v60, v158
	v_mul_f32_e32 v70, v60, v70
	v_mov_b32_e32 v60, v65
	v_mov_b32_e32 v158, v71
	v_pk_mul_f32 v[124:125], v[60:61], v[158:159]
	v_mov_b32_e32 v64, v61
	v_mov_b32_e32 v63, v124
	v_mov_b32_e32 v69, v125
	v_pk_mul_f32 v[60:61], v[64:65], v[158:159]
	v_pk_add_f32 v[68:69], v[62:63], v[68:69] neg_lo:[0,1] neg_hi:[0,1]
	v_mov_b32_e32 v71, v60
	v_mov_b32_e32 v81, v61
	v_pk_add_f32 v[60:61], v[70:71], v[80:81]
	v_mov_b32_e32 v62, v72
	v_mov_b32_e32 v63, v73
	v_mov_b32_e32 v64, v68
	v_mov_b32_e32 v65, v69

; DI unsigned cvtpk(float lo, float hi) { unsigned r; asm volatile("v_cvt_pk_bf16_f32 %0, %1, %2" : "=v"(r) : "v"(lo), "v"(hi)); return r; }
; DI bf16_t f2bf(float f) { return (bf16_t)(cvtpk(f, 0.f) & 0xffffu); }
; DI void rope128(f32x4& v0, f32x4& v1, const float* ropeA, int pos, int fq) {
;   const f32x4 cs = *(const f32x4*)(ropeA + pos * 32 + 4 * fq), sn = *(const f32x4*)(ropeA + pos * 32 + 16 + 4 * fq);
; #pragma unroll
;   for (int j = 0; j < 4; ++j) { const float x1 = v0[j], x2 = v1[j]; v0[j] = x1 * cs[j] - x2 * sn[j]; v1[j] = x2 * cs[j] + x1 * sn[j]; }
; }
; DI void store_vt(bf16_t* base  , int d0, int pos, const f32x4& v) {
; #pragma unroll
;   for (int j = 0; j < 4; ++j) base[(size_t)(d0 + j) * SL + pos] = f2bf(v[j]);
;   DI void operator()(const AccT& acc, const Unit& u, int wr, int wc, int fr, int fq) const {
;     ...
;           const float s = srow[row];
;           f32x4 v0 = acc[ai][bj][m][0] * s, v1 = acc[ai][bj][m][1] * s;
;           const int cin = wc * 32 + 4 * fq;
;           if (cb < 8) { if (wc == 0) rope128(v0, v1, ropeA, pos, fq);
;             bf16_t* dp = ak + (size_t)row * 1024 + cb * 128 + cin;
;             *(u32x2*)dp = (u32x2){cvtpk(v0[0], v0[1]), cvtpk(v0[2], v0[3])}; *(u32x2*)(dp + 16) = (u32x2){cvtpk(v1[0], v1[1]), cvtpk(v1[2], v1[3])}; }
;           else { bf16_t* base = avT + (size_t)((b * 8 + (cb - 8)) * 128) * SL; store_vt(base, cin, pos, v0); store_vt(base, cin + 16, pos, v1); }
.LBB0_880:
	v_mov_b32_e32 v0, v218
	v_cndmask_b32_e64 v58, 0, 1, s[22:23]
	v_cmp_ne_u32_e64 s[4:5], 1, v58
	s_andn2_b64 vcc, exec, s[22:23]
	s_mov_b64 s[22:23], -1
	v_pk_mul_f32 v[56:57], v[56:57], v[0:1] op_sel_hi:[1,0]
	v_pk_mul_f32 v[54:55], v[54:55], v[0:1] op_sel_hi:[1,0]
	v_pk_mul_f32 v[52:53], v[52:53], v[0:1] op_sel_hi:[1,0]
	v_pk_mul_f32 v[50:51], v[50:51], v[0:1] op_sel_hi:[1,0]
	s_cbranch_vccnz .LBB0_882
	v_readlane_b32 s22, v251, 0
	s_add_u32 s22, s22, s20
	v_readlane_b32 s23, v251, 1
	s_addc_u32 s23, s23, s21
	v_mov_b32_e32 v117, v1
	v_cvt_pk_bf16_f32 v0, v54, v1
	v_lshl_add_u64 v[58:59], s[22:23], 0, v[116:117]
	s_nop 1
	global_store_short v116, v0, s[22:23]
	s_movk_i32 s22, 0x2000
	v_add_co_u32_e32 v60, vcc, s22, v58
	v_cvt_pk_bf16_f32 v0, v55, v1
	s_movk_i32 s22, 0x6000
	s_nop 0
	v_addc_co_u32_e32 v61, vcc, 0, v59, vcc
	global_store_short v[60:61], v0, off
	v_add_co_u32_e32 v60, vcc, s82, v58
	v_cvt_pk_bf16_f32 v0, v56, v1
	s_nop 1
	v_addc_co_u32_e32 v61, vcc, 0, v59, vcc
	global_store_short v[60:61], v0, off
	v_add_co_u32_e32 v60, vcc, s22, v58
	s_mov_b32 s22, 0x20000
	s_nop 0
	v_addc_co_u32_e32 v61, vcc, 0, v59, vcc
	v_cvt_pk_bf16_f32 v0, v57, v1
	global_store_short v[60:61], v0, off
	v_add_co_u32_e32 v60, vcc, s22, v58
	s_mov_b32 s22, 0x22000
	s_nop 0
	v_addc_co_u32_e32 v61, vcc, 0, v59, vcc
	v_cvt_pk_bf16_f32 v0, v50, v1
	global_store_short v[60:61], v0, off
	v_add_co_u32_e32 v60, vcc, s22, v58
	v_cvt_pk_bf16_f32 v0, v51, v1
	s_mov_b64 s[22:23], 0
	s_nop 0
	v_addc_co_u32_e32 v61, vcc, 0, v59, vcc
	global_store_short v[60:61], v0, off
	v_add_co_u32_e32 v60, vcc, 0x24000, v58
	v_cvt_pk_bf16_f32 v0, v52, v1
	s_nop 1
	v_addc_co_u32_e32 v61, vcc, 0, v59, vcc
	v_add_co_u32_e32 v58, vcc, 0x26000, v58
	global_store_short v[60:61], v0, off
	s_nop 0
	v_addc_co_u32_e32 v59, vcc, 0, v59, vcc
	v_cvt_pk_bf16_f32 v0, v53, v1
	global_store_short v[58:59], v0, off
.LBB0_882:
	s_andn2_b64 vcc, exec, s[22:23]
	s_cbranch_vccnz .LBB0_886
	s_and_b64 vcc, exec, s[0:1]
	s_cbranch_vccnz .LBB0_885
	v_lshlrev_b32_e32 v0, 7, v150
	v_lshl_add_u64 v[62:63], v[140:141], 0, v[0:1]
	v_mov_b32_e32 v58, v176
	v_mov_b32_e32 v59, v177
	v_mov_b32_e32 v60, v178
	v_mov_b32_e32 v61, v179
	v_mov_b32_e32 v62, v180
	v_mov_b32_e32 v63, v181
	v_mov_b32_e32 v64, v182
	v_mov_b32_e32 v65, v183
	v_pk_mul_f32 v[68:69], v[50:51], v[62:63]
	s_nop 0
	v_pk_fma_f32 v[68:69], v[54:55], v[58:59], v[68:69] neg_lo:[0,0,1] neg_hi:[0,0,1]
	v_pk_mul_f32 v[54:55], v[54:55], v[62:63]
	v_mul_f32_e32 v62, v56, v64
	v_pk_fma_f32 v[50:51], v[50:51], v[58:59], v[54:55]
	v_mul_f32_e32 v54, v56, v60
	v_mul_f32_e32 v58, v52, v64
	v_mul_f32_e32 v60, v52, v60
	v_mov_b32_e32 v52, v57
	v_mov_b32_e32 v64, v61
	v_pk_mul_f32 v[70:71], v[52:53], v[64:65]
	v_mov_b32_e32 v56, v53
	v_mov_b32_e32 v55, v70
	v_mov_b32_e32 v59, v71
	v_pk_mul_f32 v[52:53], v[56:57], v[64:65]
	v_pk_add_f32 v[58:59], v[54:55], v[58:59] neg_lo:[0,1] neg_hi:[0,1]
	v_mov_b32_e32 v61, v52
	v_mov_b32_e32 v63, v53
	v_pk_add_f32 v[52:53], v[60:61], v[62:63]
	v_mov_b32_e32 v54, v68
	v_mov_b32_e32 v55, v69
	v_mov_b32_e32 v56, v58
	v_mov_b32_e32 v57, v59

; DI unsigned cvtpk(float lo, float hi) { unsigned r; asm volatile("v_cvt_pk_bf16_f32 %0, %1, %2" : "=v"(r) : "v"(lo), "v"(hi)); return r; }
; DI bf16_t f2bf(float f) { return (bf16_t)(cvtpk(f, 0.f) & 0xffffu); }
; DI void rope128(f32x4& v0, f32x4& v1, const float* ropeA, int pos, int fq) {
;   const f32x4 cs = *(const f32x4*)(ropeA + pos * 32 + 4 * fq), sn = *(const f32x4*)(ropeA + pos * 32 + 16 + 4 * fq);
; #pragma unroll
;   for (int j = 0; j < 4; ++j) { const float x1 = v0[j], x2 = v1[j]; v0[j] = x1 * cs[j] - x2 * sn[j]; v1[j] = x2 * cs[j] + x1 * sn[j]; }
; }
; DI void store_vt(bf16_t* base  , int d0, int pos, const f32x4& v) {
; #pragma unroll
;   for (int j = 0; j < 4; ++j) base[(size_t)(d0 + j) * SL + pos] = f2bf(v[j]);
;   DI void operator()(const AccT& acc, const Unit& u, int wr, int wc, int fr, int fq) const {
;     ...
;           const float s = srow[row];
;           f32x4 v0 = acc[ai][bj][m][0] * s, v1 = acc[ai][bj][m][1] * s;
;           const int cin = wc * 32 + 4 * fq;
;           if (cb < 8) { if (wc == 0) rope128(v0, v1, ropeA, pos, fq);
;             bf16_t* dp = ak + (size_t)row * 1024 + cb * 128 + cin;
;             *(u32x2*)dp = (u32x2){cvtpk(v0[0], v0[1]), cvtpk(v0[2], v0[3])}; *(u32x2*)(dp + 16) = (u32x2){cvtpk(v1[0], v1[1]), cvtpk(v1[2], v1[3])}; }
;           else { bf16_t* base = avT + (size_t)((b * 8 + (cb - 8)) * 128) * SL; store_vt(base, cin, pos, v0); store_vt(base, cin + 16, pos, v1); }
.LBB0_886:
	v_mov_b32_e32 v0, v219
	s_and_b64 vcc, exec, s[4:5]
	s_mov_b64 s[22:23], -1
	v_pk_mul_f32 v[48:49], v[48:49], v[0:1] op_sel_hi:[1,0]
	v_pk_mul_f32 v[46:47], v[46:47], v[0:1] op_sel_hi:[1,0]
	v_pk_mul_f32 v[44:45], v[44:45], v[0:1] op_sel_hi:[1,0]
	v_pk_mul_f32 v[42:43], v[42:43], v[0:1] op_sel_hi:[1,0]
	s_cbranch_vccnz .LBB0_888
	v_readlane_b32 s22, v251, 0
	s_add_u32 s22, s22, s20
	v_readlane_b32 s23, v251, 1
	s_addc_u32 s23, s23, s21
	v_mov_b32_e32 v109, v1
	v_cvt_pk_bf16_f32 v0, v46, v1
	v_lshl_add_u64 v[50:51], s[22:23], 0, v[108:109]
	s_nop 1
	global_store_short v108, v0, s[22:23]
	s_movk_i32 s22, 0x2000
	v_add_co_u32_e32 v52, vcc, s22, v50
	v_cvt_pk_bf16_f32 v0, v47, v1
	s_movk_i32 s22, 0x6000
	s_nop 0
	v_addc_co_u32_e32 v53, vcc, 0, v51, vcc
	global_store_short v[52:53], v0, off
	v_add_co_u32_e32 v52, vcc, s82, v50
	v_cvt_pk_bf16_f32 v0, v48, v1
	s_nop 1
	v_addc_co_u32_e32 v53, vcc, 0, v51, vcc
	global_store_short v[52:53], v0, off
	v_add_co_u32_e32 v52, vcc, s22, v50
	s_mov_b32 s22, 0x20000
	s_nop 0
	v_addc_co_u32_e32 v53, vcc, 0, v51, vcc
	v_cvt_pk_bf16_f32 v0, v49, v1
	global_store_short v[52:53], v0, off
	v_add_co_u32_e32 v52, vcc, s22, v50
	s_mov_b32 s22, 0x22000
	s_nop 0
	v_addc_co_u32_e32 v53, vcc, 0, v51, vcc
	v_cvt_pk_bf16_f32 v0, v42, v1
	global_store_short v[52:53], v0, off
	v_add_co_u32_e32 v52, vcc, s22, v50
	v_cvt_pk_bf16_f32 v0, v43, v1
	s_mov_b64 s[22:23], 0
	s_nop 0
	v_addc_co_u32_e32 v53, vcc, 0, v51, vcc
	global_store_short v[52:53], v0, off
	v_add_co_u32_e32 v52, vcc, 0x24000, v50
	v_cvt_pk_bf16_f32 v0, v44, v1
	s_nop 1
	v_addc_co_u32_e32 v53, vcc, 0, v51, vcc
	v_add_co_u32_e32 v50, vcc, 0x26000, v50
	global_store_short v[52:53], v0, off
	s_nop 0
	v_addc_co_u32_e32 v51, vcc, 0, v51, vcc
	v_cvt_pk_bf16_f32 v0, v45, v1
	global_store_short v[50:51], v0, off
.LBB0_888:
	s_andn2_b64 vcc, exec, s[22:23]
	s_cbranch_vccnz .LBB0_892
	s_and_b64 vcc, exec, s[0:1]
	s_cbranch_vccnz .LBB0_891
	v_lshlrev_b32_e32 v0, 7, v128
	v_lshl_add_u64 v[54:55], v[140:141], 0, v[0:1]
	v_mov_b32_e32 v50, v184
	v_mov_b32_e32 v51, v185
	v_mov_b32_e32 v52, v186
	v_mov_b32_e32 v53, v187
	v_mov_b32_e32 v54, v188
	v_mov_b32_e32 v55, v189
	v_mov_b32_e32 v56, v190
	v_mov_b32_e32 v57, v191
	v_pk_mul_f32 v[58:59], v[42:43], v[54:55]
	s_nop 0
	v_pk_fma_f32 v[58:59], v[46:47], v[50:51], v[58:59] neg_lo:[0,0,1] neg_hi:[0,0,1]
	v_pk_mul_f32 v[46:47], v[46:47], v[54:55]
	v_mul_f32_e32 v54, v48, v56
	v_pk_fma_f32 v[42:43], v[42:43], v[50:51], v[46:47]
	v_mul_f32_e32 v46, v48, v52
	v_mul_f32_e32 v50, v44, v56
	v_mul_f32_e32 v52, v44, v52
	v_mov_b32_e32 v44, v49
	v_mov_b32_e32 v56, v53
	v_pk_mul_f32 v[60:61], v[44:45], v[56:57]
	v_mov_b32_e32 v48, v45
	v_mov_b32_e32 v47, v60
	v_mov_b32_e32 v51, v61
	v_pk_mul_f32 v[44:45], v[48:49], v[56:57]
	v_pk_add_f32 v[50:51], v[46:47], v[50:51] neg_lo:[0,1] neg_hi:[0,1]
	v_mov_b32_e32 v53, v44
	v_mov_b32_e32 v55, v45
	v_pk_add_f32 v[44:45], v[52:53], v[54:55]
	v_mov_b32_e32 v46, v58
	v_mov_b32_e32 v47, v59
	v_mov_b32_e32 v48, v50
	v_mov_b32_e32 v49, v51

; DI unsigned cvtpk(float lo, float hi) { unsigned r; asm volatile("v_cvt_pk_bf16_f32 %0, %1, %2" : "=v"(r) : "v"(lo), "v"(hi)); return r; }
; DI bf16_t f2bf(float f) { return (bf16_t)(cvtpk(f, 0.f) & 0xffffu); }
; DI void rope128(f32x4& v0, f32x4& v1, const float* ropeA, int pos, int fq) {
;   const f32x4 cs = *(const f32x4*)(ropeA + pos * 32 + 4 * fq), sn = *(const f32x4*)(ropeA + pos * 32 + 16 + 4 * fq);
; #pragma unroll
;   for (int j = 0; j < 4; ++j) { const float x1 = v0[j], x2 = v1[j]; v0[j] = x1 * cs[j] - x2 * sn[j]; v1[j] = x2 * cs[j] + x1 * sn[j]; }
; }
; DI void store_vt(bf16_t* base  , int d0, int pos, const f32x4& v) {
; #pragma unroll
;   for (int j = 0; j < 4; ++j) base[(size_t)(d0 + j) * SL + pos] = f2bf(v[j]);
; }
;   DI void operator()(const AccT& acc, const Unit& u, int wr, int wc, int fr, int fq) const {
; #pragma unroll
;     for (int bj = 0; bj < 2; ++bj) {
;       const int cb = u.pn * 2 + bj;
; #pragma unroll
;       for (int ai = 0; ai < 2; ++ai)
; #pragma unroll
;         for (int m = 0; m < 4; ++m) {
;           const int row = u.pm * BM + ai * HALF + wr * 64 + m * 16 + fr, pos = row & (SL - 1), b = row >> 12;
;           const float s = srow[row];
;           f32x4 v0 = acc[ai][bj][m][0] * s, v1 = acc[ai][bj][m][1] * s;
;           const int cin = wc * 32 + 4 * fq;
;           if (cb < 8) { if (wc == 0) rope128(v0, v1, ropeA, pos, fq);
;             bf16_t* dp = ak + (size_t)row * 1024 + cb * 128 + cin;
;             *(u32x2*)dp = (u32x2){cvtpk(v0[0], v0[1]), cvtpk(v0[2], v0[3])}; *(u32x2*)(dp + 16) = (u32x2){cvtpk(v1[0], v1[1]), cvtpk(v1[2], v1[3])}; }
;           else { bf16_t* base = avT + (size_t)((b * 8 + (cb - 8)) * 128) * SL; store_vt(base, cin, pos, v0); store_vt(base, cin + 16, pos, v1); }
;         }
;     }
;   }
.LBB0_892:
	v_mov_b32_e32 v0, v223
	s_and_b64 vcc, exec, s[4:5]
	s_mov_b64 s[22:23], -1
	v_pk_mul_f32 v[40:41], v[40:41], v[0:1] op_sel_hi:[1,0]
	v_pk_mul_f32 v[38:39], v[38:39], v[0:1] op_sel_hi:[1,0]
	v_pk_mul_f32 v[36:37], v[36:37], v[0:1] op_sel_hi:[1,0]
	v_pk_mul_f32 v[34:35], v[34:35], v[0:1] op_sel_hi:[1,0]
	s_cbranch_vccnz .LBB0_894
	v_readlane_b32 s22, v251, 0
	s_add_u32 s20, s22, s20
	v_readlane_b32 s22, v251, 1
	s_addc_u32 s21, s22, s21
	v_mov_b32_e32 v101, v1
	v_cvt_pk_bf16_f32 v0, v38, v1
	v_lshl_add_u64 v[42:43], s[20:21], 0, v[100:101]
	global_store_short v100, v0, s[20:21]
	s_movk_i32 s20, 0x2000
	v_add_co_u32_e32 v44, vcc, s20, v42
	v_cvt_pk_bf16_f32 v0, v39, v1
	s_movk_i32 s20, 0x6000
	s_nop 0
	v_addc_co_u32_e32 v45, vcc, 0, v43, vcc
	global_store_short v[44:45], v0, off
	v_add_co_u32_e32 v44, vcc, s82, v42
	v_cvt_pk_bf16_f32 v0, v40, v1
	s_mov_b64 s[22:23], 0
	s_nop 0
	v_addc_co_u32_e32 v45, vcc, 0, v43, vcc
	global_store_short v[44:45], v0, off
	v_add_co_u32_e32 v44, vcc, s20, v42
	s_mov_b32 s20, 0x20000
	s_nop 0
	v_addc_co_u32_e32 v45, vcc, 0, v43, vcc
	v_cvt_pk_bf16_f32 v0, v41, v1
	global_store_short v[44:45], v0, off
	v_add_co_u32_e32 v44, vcc, s20, v42
	s_mov_b32 s20, 0x22000
	s_nop 0
	v_addc_co_u32_e32 v45, vcc, 0, v43, vcc
	v_cvt_pk_bf16_f32 v0, v34, v1
	global_store_short v[44:45], v0, off
	v_add_co_u32_e32 v44, vcc, s20, v42
	v_cvt_pk_bf16_f32 v0, v35, v1
	s_nop 1
	v_addc_co_u32_e32 v45, vcc, 0, v43, vcc
	global_store_short v[44:45], v0, off
	v_add_co_u32_e32 v44, vcc, 0x24000, v42
	v_cvt_pk_bf16_f32 v0, v36, v1
	s_nop 1
	v_addc_co_u32_e32 v45, vcc, 0, v43, vcc
	v_add_co_u32_e32 v42, vcc, 0x26000, v42
	global_store_short v[44:45], v0, off
	s_nop 0
	v_addc_co_u32_e32 v43, vcc, 0, v43, vcc
	v_cvt_pk_bf16_f32 v0, v37, v1
	global_store_short v[42:43], v0, off
.LBB0_894:
	s_andn2_b64 vcc, exec, s[22:23]
	s_cbranch_vccnz .LBB0_898
	s_and_b64 vcc, exec, s[0:1]
	s_cbranch_vccnz .LBB0_897
	v_lshlrev_b32_e32 v0, 7, v120
	v_lshl_add_u64 v[46:47], v[140:141], 0, v[0:1]
	v_mov_b32_e32 v42, v192
	v_mov_b32_e32 v43, v193
	v_mov_b32_e32 v44, v194
	v_mov_b32_e32 v45, v195
	v_mov_b32_e32 v46, v196
	v_mov_b32_e32 v47, v197
	v_mov_b32_e32 v48, v198
	v_mov_b32_e32 v49, v199
	v_pk_mul_f32 v[50:51], v[34:35], v[46:47]
	s_nop 0
	v_pk_fma_f32 v[50:51], v[38:39], v[42:43], v[50:51] neg_lo:[0,0,1] neg_hi:[0,0,1]
	v_pk_mul_f32 v[38:39], v[38:39], v[46:47]
	v_mul_f32_e32 v46, v40, v48
	v_pk_fma_f32 v[34:35], v[34:35], v[42:43], v[38:39]
	v_mul_f32_e32 v38, v40, v44
	v_mul_f32_e32 v42, v36, v48
	v_mul_f32_e32 v44, v36, v44
	v_mov_b32_e32 v36, v41
	v_mov_b32_e32 v48, v45
	v_pk_mul_f32 v[52:53], v[36:37], v[48:49]
	v_mov_b32_e32 v40, v37
	v_mov_b32_e32 v39, v52
	v_mov_b32_e32 v43, v53
	v_pk_mul_f32 v[36:37], v[40:41], v[48:49]
	v_pk_add_f32 v[42:43], v[38:39], v[42:43] neg_lo:[0,1] neg_hi:[0,1]
	v_mov_b32_e32 v45, v36
	v_mov_b32_e32 v47, v37
	v_pk_add_f32 v[36:37], v[44:45], v[46:47]
	v_mov_b32_e32 v38, v50
	v_mov_b32_e32 v39, v51
	v_mov_b32_e32 v40, v42
	v_mov_b32_e32 v41, v43

; DI unsigned cvtpk(float lo, float hi) { unsigned r; asm volatile("v_cvt_pk_bf16_f32 %0, %1, %2" : "=v"(r) : "v"(lo), "v"(hi)); return r; }
; DI bf16_t f2bf(float f) { return (bf16_t)(cvtpk(f, 0.f) & 0xffffu); }
; DI void rope128(f32x4& v0, f32x4& v1, const float* ropeA, int pos, int fq) {
;   const f32x4 cs = *(const f32x4*)(ropeA + pos * 32 + 4 * fq), sn = *(const f32x4*)(ropeA + pos * 32 + 16 + 4 * fq);
; #pragma unroll
;   for (int j = 0; j < 4; ++j) { const float x1 = v0[j], x2 = v1[j]; v0[j] = x1 * cs[j] - x2 * sn[j]; v1[j] = x2 * cs[j] + x1 * sn[j]; }
; }
; DI void store_vt(bf16_t* base  , int d0, int pos, const f32x4& v) {
; #pragma unroll
;   for (int j = 0; j < 4; ++j) base[(size_t)(d0 + j) * SL + pos] = f2bf(v[j]);
; }
;   DI void operator()(const AccT& acc, const Unit& u, int wr, int wc, int fr, int fq) const {
; #pragma unroll
;     for (int bj = 0; bj < 2; ++bj) {
;       const int cb = u.pn * 2 + bj;
; #pragma unroll
;       for (int ai = 0; ai < 2; ++ai)
; #pragma unroll
;         for (int m = 0; m < 4; ++m) {
;           const int row = u.pm * BM + ai * HALF + wr * 64 + m * 16 + fr, pos = row & (SL - 1), b = row >> 12;
;           const float s = srow[row];
;           f32x4 v0 = acc[ai][bj][m][0] * s, v1 = acc[ai][bj][m][1] * s;
;           const int cin = wc * 32 + 4 * fq;
;           if (cb < 8) { if (wc == 0) rope128(v0, v1, ropeA, pos, fq);
;             bf16_t* dp = ak + (size_t)row * 1024 + cb * 128 + cin;
;             *(u32x2*)dp = (u32x2){cvtpk(v0[0], v0[1]), cvtpk(v0[2], v0[3])}; *(u32x2*)(dp + 16) = (u32x2){cvtpk(v1[0], v1[1]), cvtpk(v1[2], v1[3])}; }
;           else { bf16_t* base = avT + (size_t)((b * 8 + (cb - 8)) * 128) * SL; store_vt(base, cin, pos, v0); store_vt(base, cin + 16, pos, v1); }
;         }
;     }
;   }
.LBB0_898:
	v_mov_b32_e32 v0, v228
	s_add_i32 s24, s24, s13
	s_lshl_b32 s20, s24, 7
	s_ashr_i32 s21, s20, 31
	s_and_b64 vcc, exec, s[4:5]
	s_lshl_b64 s[20:21], s[20:21], 13
	s_mov_b64 s[22:23], -1
	v_pk_mul_f32 v[32:33], v[32:33], v[0:1] op_sel_hi:[1,0]
	v_pk_mul_f32 v[30:31], v[30:31], v[0:1] op_sel_hi:[1,0]
	v_pk_mul_f32 v[28:29], v[28:29], v[0:1] op_sel_hi:[1,0]
	v_pk_mul_f32 v[26:27], v[26:27], v[0:1] op_sel_hi:[1,0]
	s_cbranch_vccnz .LBB0_900
	v_readlane_b32 s13, v251, 0
	s_add_u32 s22, s13, s20
	v_readlane_b32 s13, v251, 1
	s_addc_u32 s23, s13, s21
	v_mov_b32_e32 v93, v1
	v_lshl_add_u64 v[34:35], s[22:23], 0, v[92:93]
	s_movk_i32 s13, 0x2000
	v_add_co_u32_e32 v36, vcc, s13, v34
	v_cvt_pk_bf16_f32 v0, v30, v1
	global_store_short v92, v0, s[22:23]
	s_nop 0
	v_addc_co_u32_e32 v37, vcc, 0, v35, vcc
	v_cvt_pk_bf16_f32 v0, v31, v1
	global_store_short v[36:37], v0, off
	v_add_co_u32_e32 v36, vcc, s82, v34
	s_movk_i32 s13, 0x6000
	s_nop 0
	v_addc_co_u32_e32 v37, vcc, 0, v35, vcc
	v_cvt_pk_bf16_f32 v0, v32, v1
	global_store_short v[36:37], v0, off
	v_add_co_u32_e32 v36, vcc, s13, v34
	s_mov_b32 s13, 0x20000
	s_nop 0
	v_addc_co_u32_e32 v37, vcc, 0, v35, vcc
	v_cvt_pk_bf16_f32 v0, v33, v1
	global_store_short v[36:37], v0, off
	v_add_co_u32_e32 v36, vcc, s13, v34
	s_mov_b32 s13, 0x22000
	s_nop 0
	v_addc_co_u32_e32 v37, vcc, 0, v35, vcc
	v_cvt_pk_bf16_f32 v0, v26, v1
	global_store_short v[36:37], v0, off
	v_add_co_u32_e32 v36, vcc, s13, v34
	v_cvt_pk_bf16_f32 v0, v27, v1
	s_mov_b64 s[22:23], 0
	s_nop 0
	v_addc_co_u32_e32 v37, vcc, 0, v35, vcc
	global_store_short v[36:37], v0, off
	v_add_co_u32_e32 v36, vcc, 0x24000, v34
	v_cvt_pk_bf16_f32 v0, v28, v1
	s_nop 1
	v_addc_co_u32_e32 v37, vcc, 0, v35, vcc
	v_add_co_u32_e32 v34, vcc, 0x26000, v34
	global_store_short v[36:37], v0, off
	s_nop 0
	v_addc_co_u32_e32 v35, vcc, 0, v35, vcc
	v_cvt_pk_bf16_f32 v0, v29, v1
	global_store_short v[34:35], v0, off
.LBB0_900:
	s_andn2_b64 vcc, exec, s[22:23]
	s_cbranch_vccnz .LBB0_904
	s_and_b64 vcc, exec, s[0:1]
	s_cbranch_vccnz .LBB0_903
	v_lshlrev_b32_e32 v0, 7, v112
	v_lshl_add_u64 v[38:39], v[140:141], 0, v[0:1]
	v_mov_b32_e32 v34, v200
	v_mov_b32_e32 v35, v201
	v_mov_b32_e32 v36, v202
	v_mov_b32_e32 v37, v203
	v_mov_b32_e32 v38, v204
	v_mov_b32_e32 v39, v205
	v_mov_b32_e32 v40, v206
	v_mov_b32_e32 v41, v207
	v_pk_mul_f32 v[42:43], v[26:27], v[38:39]
	s_nop 0
	v_pk_fma_f32 v[42:43], v[30:31], v[34:35], v[42:43] neg_lo:[0,0,1] neg_hi:[0,0,1]
	v_pk_mul_f32 v[30:31], v[30:31], v[38:39]
	v_mul_f32_e32 v38, v32, v40
	v_pk_fma_f32 v[26:27], v[26:27], v[34:35], v[30:31]
	v_mul_f32_e32 v30, v32, v36
	v_mul_f32_e32 v34, v28, v40
	v_mul_f32_e32 v36, v28, v36
	v_mov_b32_e32 v28, v33
	v_mov_b32_e32 v40, v37
	v_pk_mul_f32 v[44:45], v[28:29], v[40:41]
	v_mov_b32_e32 v32, v29
	v_mov_b32_e32 v31, v44
	v_mov_b32_e32 v35, v45
	v_pk_mul_f32 v[28:29], v[32:33], v[40:41]
	v_pk_add_f32 v[34:35], v[30:31], v[34:35] neg_lo:[0,1] neg_hi:[0,1]
	v_mov_b32_e32 v37, v28
	v_mov_b32_e32 v39, v29
	v_pk_add_f32 v[28:29], v[36:37], v[38:39]
	v_mov_b32_e32 v30, v42
	v_mov_b32_e32 v31, v43
	v_mov_b32_e32 v32, v34
	v_mov_b32_e32 v33, v35

; DI unsigned cvtpk(float lo, float hi) { unsigned r; asm volatile("v_cvt_pk_bf16_f32 %0, %1, %2" : "=v"(r) : "v"(lo), "v"(hi)); return r; }
; DI bf16_t f2bf(float f) { return (bf16_t)(cvtpk(f, 0.f) & 0xffffu); }
; DI void rope128(f32x4& v0, f32x4& v1, const float* ropeA, int pos, int fq) {
;   const f32x4 cs = *(const f32x4*)(ropeA + pos * 32 + 4 * fq), sn = *(const f32x4*)(ropeA + pos * 32 + 16 + 4 * fq);
; #pragma unroll
;   for (int j = 0; j < 4; ++j) { const float x1 = v0[j], x2 = v1[j]; v0[j] = x1 * cs[j] - x2 * sn[j]; v1[j] = x2 * cs[j] + x1 * sn[j]; }
; }
; DI void store_vt(bf16_t* base  , int d0, int pos, const f32x4& v) {
; #pragma unroll
;   for (int j = 0; j < 4; ++j) base[(size_t)(d0 + j) * SL + pos] = f2bf(v[j]);
; }
;   DI void operator()(const AccT& acc, const Unit& u, int wr, int wc, int fr, int fq) const {
; #pragma unroll
;     for (int bj = 0; bj < 2; ++bj) {
;       const int cb = u.pn * 2 + bj;
; #pragma unroll
;       for (int ai = 0; ai < 2; ++ai)
; #pragma unroll
;         for (int m = 0; m < 4; ++m) {
;           const int row = u.pm * BM + ai * HALF + wr * 64 + m * 16 + fr, pos = row & (SL - 1), b = row >> 12;
;           const float s = srow[row];
;           f32x4 v0 = acc[ai][bj][m][0] * s, v1 = acc[ai][bj][m][1] * s;
;           const int cin = wc * 32 + 4 * fq;
;           if (cb < 8) { if (wc == 0) rope128(v0, v1, ropeA, pos, fq);
;             bf16_t* dp = ak + (size_t)row * 1024 + cb * 128 + cin;
;             *(u32x2*)dp = (u32x2){cvtpk(v0[0], v0[1]), cvtpk(v0[2], v0[3])}; *(u32x2*)(dp + 16) = (u32x2){cvtpk(v1[0], v1[1]), cvtpk(v1[2], v1[3])}; }
;           else { bf16_t* base = avT + (size_t)((b * 8 + (cb - 8)) * 128) * SL; store_vt(base, cin, pos, v0); store_vt(base, cin + 16, pos, v1); }
;         }
;     }
;   }
.LBB0_904:
	v_mov_b32_e32 v0, v231
	s_and_b64 vcc, exec, s[4:5]
	s_mov_b64 s[22:23], -1
	v_pk_mul_f32 v[24:25], v[24:25], v[0:1] op_sel_hi:[1,0]
	v_pk_mul_f32 v[22:23], v[22:23], v[0:1] op_sel_hi:[1,0]
	v_pk_mul_f32 v[20:21], v[20:21], v[0:1] op_sel_hi:[1,0]
	v_pk_mul_f32 v[18:19], v[18:19], v[0:1] op_sel_hi:[1,0]
	s_cbranch_vccnz .LBB0_906
	v_readlane_b32 s13, v251, 0
	s_add_u32 s22, s13, s20
	v_readlane_b32 s13, v251, 1
	s_addc_u32 s23, s13, s21
	v_mov_b32_e32 v85, v1
	v_lshl_add_u64 v[26:27], s[22:23], 0, v[84:85]
	s_movk_i32 s13, 0x2000
	v_add_co_u32_e32 v28, vcc, s13, v26
	v_cvt_pk_bf16_f32 v0, v22, v1
	global_store_short v84, v0, s[22:23]
	s_nop 0
	v_addc_co_u32_e32 v29, vcc, 0, v27, vcc
	v_cvt_pk_bf16_f32 v0, v23, v1
	global_store_short v[28:29], v0, off
	v_add_co_u32_e32 v28, vcc, s82, v26
	s_movk_i32 s13, 0x6000
	s_nop 0
	v_addc_co_u32_e32 v29, vcc, 0, v27, vcc
	v_cvt_pk_bf16_f32 v0, v24, v1
	global_store_short v[28:29], v0, off
	v_add_co_u32_e32 v28, vcc, s13, v26
	s_mov_b32 s13, 0x20000
	s_nop 0
	v_addc_co_u32_e32 v29, vcc, 0, v27, vcc
	v_cvt_pk_bf16_f32 v0, v25, v1
	global_store_short v[28:29], v0, off
	v_add_co_u32_e32 v28, vcc, s13, v26
	s_mov_b32 s13, 0x22000
	s_nop 0
	v_addc_co_u32_e32 v29, vcc, 0, v27, vcc
	v_cvt_pk_bf16_f32 v0, v18, v1
	global_store_short v[28:29], v0, off
	v_add_co_u32_e32 v28, vcc, s13, v26
	v_cvt_pk_bf16_f32 v0, v19, v1
	s_mov_b64 s[22:23], 0
	s_nop 0
	v_addc_co_u32_e32 v29, vcc, 0, v27, vcc
	global_store_short v[28:29], v0, off
	v_add_co_u32_e32 v28, vcc, 0x24000, v26
	v_cvt_pk_bf16_f32 v0, v20, v1
	s_nop 1
	v_addc_co_u32_e32 v29, vcc, 0, v27, vcc
	v_add_co_u32_e32 v26, vcc, 0x26000, v26
	global_store_short v[28:29], v0, off
	s_nop 0
	v_addc_co_u32_e32 v27, vcc, 0, v27, vcc
	v_cvt_pk_bf16_f32 v0, v21, v1
	global_store_short v[26:27], v0, off
.LBB0_906:
	s_andn2_b64 vcc, exec, s[22:23]
	s_cbranch_vccnz .LBB0_910
	s_and_b64 vcc, exec, s[0:1]
	s_cbranch_vccnz .LBB0_909
	v_lshlrev_b32_e32 v0, 7, v104
	v_lshl_add_u64 v[30:31], v[140:141], 0, v[0:1]
	v_mov_b32_e32 v26, v208
	v_mov_b32_e32 v27, v209
	v_mov_b32_e32 v28, v210
	v_mov_b32_e32 v29, v211
	v_mov_b32_e32 v30, v214
	v_mov_b32_e32 v31, v215
	v_mov_b32_e32 v32, v216
	v_mov_b32_e32 v33, v217
	v_pk_mul_f32 v[34:35], v[18:19], v[30:31]
	s_nop 0
	v_pk_fma_f32 v[34:35], v[22:23], v[26:27], v[34:35] neg_lo:[0,0,1] neg_hi:[0,0,1]
	v_pk_mul_f32 v[22:23], v[22:23], v[30:31]
	v_mul_f32_e32 v30, v24, v32
	v_pk_fma_f32 v[18:19], v[18:19], v[26:27], v[22:23]
	v_mul_f32_e32 v22, v24, v28
	v_mul_f32_e32 v26, v20, v32
	v_mul_f32_e32 v28, v20, v28
	v_mov_b32_e32 v20, v25
	v_mov_b32_e32 v32, v29
	v_pk_mul_f32 v[36:37], v[20:21], v[32:33]
	v_mov_b32_e32 v24, v21
	v_mov_b32_e32 v23, v36
	v_mov_b32_e32 v27, v37
	v_pk_mul_f32 v[20:21], v[24:25], v[32:33]
	v_pk_add_f32 v[26:27], v[22:23], v[26:27] neg_lo:[0,1] neg_hi:[0,1]
	v_mov_b32_e32 v29, v20
	v_mov_b32_e32 v31, v21
	v_pk_add_f32 v[20:21], v[28:29], v[30:31]
	v_mov_b32_e32 v22, v34
	v_mov_b32_e32 v23, v35
	v_mov_b32_e32 v24, v26
	v_mov_b32_e32 v25, v27

; DI unsigned cvtpk(float lo, float hi) { unsigned r; asm volatile("v_cvt_pk_bf16_f32 %0, %1, %2" : "=v"(r) : "v"(lo), "v"(hi)); return r; }
; DI bf16_t f2bf(float f) { return (bf16_t)(cvtpk(f, 0.f) & 0xffffu); }
; DI void rope128(f32x4& v0, f32x4& v1, const float* ropeA, int pos, int fq) {
;   const f32x4 cs = *(const f32x4*)(ropeA + pos * 32 + 4 * fq), sn = *(const f32x4*)(ropeA + pos * 32 + 16 + 4 * fq);
; #pragma unroll
;   for (int j = 0; j < 4; ++j) { const float x1 = v0[j], x2 = v1[j]; v0[j] = x1 * cs[j] - x2 * sn[j]; v1[j] = x2 * cs[j] + x1 * sn[j]; }
; }
; DI void store_vt(bf16_t* base  , int d0, int pos, const f32x4& v) {
; #pragma unroll
;   for (int j = 0; j < 4; ++j) base[(size_t)(d0 + j) * SL + pos] = f2bf(v[j]);
; }
;   DI void operator()(const AccT& acc, const Unit& u, int wr, int wc, int fr, int fq) const {
; #pragma unroll
;     for (int bj = 0; bj < 2; ++bj) {
;       const int cb = u.pn * 2 + bj;
; #pragma unroll
;       for (int ai = 0; ai < 2; ++ai)
; #pragma unroll
;         for (int m = 0; m < 4; ++m) {
;           const int row = u.pm * BM + ai * HALF + wr * 64 + m * 16 + fr, pos = row & (SL - 1), b = row >> 12;
;           const float s = srow[row];
;           f32x4 v0 = acc[ai][bj][m][0] * s, v1 = acc[ai][bj][m][1] * s;
;           const int cin = wc * 32 + 4 * fq;
;           if (cb < 8) { if (wc == 0) rope128(v0, v1, ropeA, pos, fq);
;             bf16_t* dp = ak + (size_t)row * 1024 + cb * 128 + cin;
;             *(u32x2*)dp = (u32x2){cvtpk(v0[0], v0[1]), cvtpk(v0[2], v0[3])}; *(u32x2*)(dp + 16) = (u32x2){cvtpk(v1[0], v1[1]), cvtpk(v1[2], v1[3])}; }
;           else { bf16_t* base = avT + (size_t)((b * 8 + (cb - 8)) * 128) * SL; store_vt(base, cin, pos, v0); store_vt(base, cin + 16, pos, v1); }
;         }
;     }
;   }
.LBB0_910:
	v_mov_b32_e32 v0, v244
	s_and_b64 vcc, exec, s[4:5]
	s_mov_b64 s[22:23], -1
	v_pk_mul_f32 v[16:17], v[16:17], v[0:1] op_sel_hi:[1,0]
	v_pk_mul_f32 v[14:15], v[14:15], v[0:1] op_sel_hi:[1,0]
	v_pk_mul_f32 v[12:13], v[12:13], v[0:1] op_sel_hi:[1,0]
	v_pk_mul_f32 v[10:11], v[10:11], v[0:1] op_sel_hi:[1,0]
	s_cbranch_vccnz .LBB0_912
	v_readlane_b32 s13, v251, 0
	s_add_u32 s22, s13, s20
	v_readlane_b32 s13, v251, 1
	s_addc_u32 s23, s13, s21
	v_mov_b32_e32 v77, v1
	v_lshl_add_u64 v[18:19], s[22:23], 0, v[76:77]
	s_movk_i32 s13, 0x2000
	v_add_co_u32_e32 v20, vcc, s13, v18
	v_cvt_pk_bf16_f32 v0, v14, v1
	global_store_short v76, v0, s[22:23]
	s_nop 0
	v_addc_co_u32_e32 v21, vcc, 0, v19, vcc
	v_cvt_pk_bf16_f32 v0, v15, v1
	global_store_short v[20:21], v0, off
	v_add_co_u32_e32 v20, vcc, s82, v18
	s_movk_i32 s13, 0x6000
	s_nop 0
	v_addc_co_u32_e32 v21, vcc, 0, v19, vcc
	v_cvt_pk_bf16_f32 v0, v16, v1
	global_store_short v[20:21], v0, off
	v_add_co_u32_e32 v20, vcc, s13, v18
	s_mov_b32 s13, 0x20000
	s_nop 0
	v_addc_co_u32_e32 v21, vcc, 0, v19, vcc
	v_cvt_pk_bf16_f32 v0, v17, v1
	global_store_short v[20:21], v0, off
	v_add_co_u32_e32 v20, vcc, s13, v18
	s_mov_b32 s13, 0x22000
	s_nop 0
	v_addc_co_u32_e32 v21, vcc, 0, v19, vcc
	v_cvt_pk_bf16_f32 v0, v10, v1
	global_store_short v[20:21], v0, off
	v_add_co_u32_e32 v20, vcc, s13, v18
	v_cvt_pk_bf16_f32 v0, v11, v1
	s_mov_b64 s[22:23], 0
	s_nop 0
	v_addc_co_u32_e32 v21, vcc, 0, v19, vcc
	global_store_short v[20:21], v0, off
	v_add_co_u32_e32 v20, vcc, 0x24000, v18
	v_cvt_pk_bf16_f32 v0, v12, v1
	s_nop 1
	v_addc_co_u32_e32 v21, vcc, 0, v19, vcc
	v_add_co_u32_e32 v18, vcc, 0x26000, v18
	global_store_short v[20:21], v0, off
	s_nop 0
	v_addc_co_u32_e32 v19, vcc, 0, v19, vcc
	v_cvt_pk_bf16_f32 v0, v13, v1
	global_store_short v[18:19], v0, off
.LBB0_912:
	s_andn2_b64 vcc, exec, s[22:23]
	s_cbranch_vccnz .LBB0_916
	s_and_b64 vcc, exec, s[0:1]
	s_cbranch_vccnz .LBB0_915
	v_lshlrev_b32_e32 v0, 7, v96
	v_lshl_add_u64 v[22:23], v[140:141], 0, v[0:1]
	v_mov_b32_e32 v18, v224
	v_mov_b32_e32 v19, v225
	v_mov_b32_e32 v20, v226
	v_mov_b32_e32 v21, v227
	v_mov_b32_e32 v22, v232
	v_mov_b32_e32 v23, v233
	v_mov_b32_e32 v24, v234
	v_mov_b32_e32 v25, v235
	v_pk_mul_f32 v[26:27], v[10:11], v[22:23]
	s_nop 0
	v_pk_fma_f32 v[26:27], v[14:15], v[18:19], v[26:27] neg_lo:[0,0,1] neg_hi:[0,0,1]
	v_pk_mul_f32 v[14:15], v[14:15], v[22:23]
	v_mul_f32_e32 v22, v16, v24
	v_pk_fma_f32 v[10:11], v[10:11], v[18:19], v[14:15]
	v_mul_f32_e32 v14, v16, v20
	v_mul_f32_e32 v18, v12, v24
	v_mul_f32_e32 v20, v12, v20
	v_mov_b32_e32 v12, v17
	v_mov_b32_e32 v24, v21
	v_pk_mul_f32 v[28:29], v[12:13], v[24:25]
	v_mov_b32_e32 v16, v13
	v_mov_b32_e32 v15, v28
	v_mov_b32_e32 v19, v29
	v_pk_mul_f32 v[12:13], v[16:17], v[24:25]
	v_pk_add_f32 v[18:19], v[14:15], v[18:19] neg_lo:[0,1] neg_hi:[0,1]
	v_mov_b32_e32 v21, v12
	v_mov_b32_e32 v23, v13
	v_pk_add_f32 v[12:13], v[20:21], v[22:23]
	v_mov_b32_e32 v14, v26
	v_mov_b32_e32 v15, v27
	v_mov_b32_e32 v16, v18
	v_mov_b32_e32 v17, v19

; DI unsigned cvtpk(float lo, float hi) { unsigned r; asm volatile("v_cvt_pk_bf16_f32 %0, %1, %2" : "=v"(r) : "v"(lo), "v"(hi)); return r; }
; DI bf16_t f2bf(float f) { return (bf16_t)(cvtpk(f, 0.f) & 0xffffu); }
; DI void store_vt(bf16_t* base  , int d0, int pos, const f32x4& v) {
; #pragma unroll
;   for (int j = 0; j < 4; ++j) base[(size_t)(d0 + j) * SL + pos] = f2bf(v[j]);
; }
;   DI void operator()(const AccT& acc, const Unit& u, int wr, int wc, int fr, int fq) const {
; #pragma unroll
;     for (int bj = 0; bj < 2; ++bj) {
;       const int cb = u.pn * 2 + bj;
; #pragma unroll
;       for (int ai = 0; ai < 2; ++ai)
; #pragma unroll
;         for (int m = 0; m < 4; ++m) {
;           const int row = u.pm * BM + ai * HALF + wr * 64 + m * 16 + fr, pos = row & (SL - 1), b = row >> 12;
;           const float s = srow[row];
;           f32x4 v0 = acc[ai][bj][m][0] * s, v1 = acc[ai][bj][m][1] * s;
;           const int cin = wc * 32 + 4 * fq;
;           if (cb < 8) { if (wc == 0) rope128(v0, v1, ropeA, pos, fq);
;             bf16_t* dp = ak + (size_t)row * 1024 + cb * 128 + cin;
;             *(u32x2*)dp = (u32x2){cvtpk(v0[0], v0[1]), cvtpk(v0[2], v0[3])}; *(u32x2*)(dp + 16) = (u32x2){cvtpk(v1[0], v1[1]), cvtpk(v1[2], v1[3])}; }
;           else { bf16_t* base = avT + (size_t)((b * 8 + (cb - 8)) * 128) * SL; store_vt(base, cin, pos, v0); store_vt(base, cin + 16, pos, v1); }
.LBB0_916:
	v_mov_b32_e32 v0, v245
	s_and_b64 vcc, exec, s[4:5]
	s_mov_b64 s[4:5], -1
	v_pk_mul_f32 v[8:9], v[8:9], v[0:1] op_sel_hi:[1,0]
	v_pk_mul_f32 v[6:7], v[6:7], v[0:1] op_sel_hi:[1,0]
	v_pk_mul_f32 v[4:5], v[4:5], v[0:1] op_sel_hi:[1,0]
	v_pk_mul_f32 v[2:3], v[2:3], v[0:1] op_sel_hi:[1,0]
	s_cbranch_vccnz .LBB0_919
	v_readlane_b32 s4, v251, 0
	s_add_u32 s4, s4, s20
	v_readlane_b32 s5, v251, 1
	s_addc_u32 s5, s5, s21
	v_mov_b32_e32 v67, v1
	v_cvt_pk_bf16_f32 v0, v6, v1
	v_lshl_add_u64 v[10:11], s[4:5], 0, v[66:67]
	s_nop 1
	global_store_short v66, v0, s[4:5]
	s_movk_i32 s4, 0x2000
	v_add_co_u32_e32 v12, vcc, s4, v10
	v_cvt_pk_bf16_f32 v0, v7, v1
	s_movk_i32 s4, 0x6000
	s_nop 0
	v_addc_co_u32_e32 v13, vcc, 0, v11, vcc
	global_store_short v[12:13], v0, off
	v_add_co_u32_e32 v12, vcc, s82, v10
	v_cvt_pk_bf16_f32 v0, v8, v1
	s_nop 1
	v_addc_co_u32_e32 v13, vcc, 0, v11, vcc
	global_store_short v[12:13], v0, off
	v_add_co_u32_e32 v12, vcc, s4, v10
	s_mov_b32 s4, 0x20000
	s_nop 0
	v_addc_co_u32_e32 v13, vcc, 0, v11, vcc
	v_cvt_pk_bf16_f32 v0, v9, v1
	global_store_short v[12:13], v0, off
	v_add_co_u32_e32 v12, vcc, s4, v10
	s_mov_b32 s4, 0x22000
	s_nop 0
	v_addc_co_u32_e32 v13, vcc, 0, v11, vcc
	v_cvt_pk_bf16_f32 v0, v2, v1
	global_store_short v[12:13], v0, off
	v_add_co_u32_e32 v12, vcc, s4, v10
	v_cvt_pk_bf16_f32 v0, v3, v1
	s_nop 1
	v_addc_co_u32_e32 v13, vcc, 0, v11, vcc
	global_store_short v[12:13], v0, off
	v_add_co_u32_e32 v12, vcc, 0x24000, v10
	v_cvt_pk_bf16_f32 v0, v4, v1
	s_nop 1
	v_addc_co_u32_e32 v13, vcc, 0, v11, vcc
	v_add_co_u32_e32 v10, vcc, 0x26000, v10
	global_store_short v[12:13], v0, off
	s_nop 0
	v_addc_co_u32_e32 v11, vcc, 0, v11, vcc
	v_cvt_pk_bf16_f32 v0, v5, v1
	global_store_short v[10:11], v0, off
	s_cbranch_execz .LBB0_920

; DI void rope128(f32x4& v0, f32x4& v1, const float* ropeA, int pos, int fq) {
;   const f32x4 cs = *(const f32x4*)(ropeA + pos * 32 + 4 * fq), sn = *(const f32x4*)(ropeA + pos * 32 + 16 + 4 * fq);
; #pragma unroll
;   for (int j = 0; j < 4; ++j) { const float x1 = v0[j], x2 = v1[j]; v0[j] = x1 * cs[j] - x2 * sn[j]; v1[j] = x2 * cs[j] + x1 * sn[j]; }
; }
;   DI void operator()(const AccT& acc, const Unit& u, int wr, int wc, int fr, int fq) const {
;     ...
;           if (cb < 8) { if (wc == 0) rope128(v0, v1, ropeA, pos, fq);
.LBB0_920:
	s_and_b64 vcc, exec, s[0:1]
	s_cbranch_vccnz .LBB0_922
	v_lshlrev_b32_e32 v0, 7, v88
	v_lshl_add_u64 v[14:15], v[140:141], 0, v[0:1]
	v_mov_b32_e32 v10, v236
	v_mov_b32_e32 v11, v237
	v_mov_b32_e32 v12, v238
	v_mov_b32_e32 v13, v239
	v_mov_b32_e32 v14, v240
	v_mov_b32_e32 v15, v241
	v_mov_b32_e32 v16, v242
	v_mov_b32_e32 v17, v243
	v_pk_mul_f32 v[18:19], v[2:3], v[14:15]
	s_nop 0
	v_pk_fma_f32 v[18:19], v[6:7], v[10:11], v[18:19] neg_lo:[0,0,1] neg_hi:[0,0,1]
	v_pk_mul_f32 v[6:7], v[6:7], v[14:15]
	v_mul_f32_e32 v14, v8, v16
	v_pk_fma_f32 v[2:3], v[2:3], v[10:11], v[6:7]
	v_mul_f32_e32 v6, v8, v12
	v_mul_f32_e32 v10, v4, v16
	v_mul_f32_e32 v12, v4, v12
	v_mov_b32_e32 v4, v9
	v_mov_b32_e32 v16, v13
	v_pk_mul_f32 v[20:21], v[4:5], v[16:17]
	v_mov_b32_e32 v8, v5
	v_mov_b32_e32 v7, v20
	v_mov_b32_e32 v11, v21
	v_pk_mul_f32 v[4:5], v[8:9], v[16:17]
	v_pk_add_f32 v[10:11], v[6:7], v[10:11] neg_lo:[0,1] neg_hi:[0,1]
	v_mov_b32_e32 v13, v4
	v_mov_b32_e32 v15, v5
	v_pk_add_f32 v[4:5], v[12:13], v[14:15]
	v_mov_b32_e32 v6, v18
	v_mov_b32_e32 v7, v19
	v_mov_b32_e32 v8, v10
	v_mov_b32_e32 v9, v11

; DI unsigned cvtpk(float lo, float hi) { unsigned r; asm volatile("v_cvt_pk_bf16_f32 %0, %1, %2" : "=v"(r) : "v"(lo), "v"(hi)); return r; }
; DI float bf2f(bf16_t b) { return __uint_as_float(((unsigned)b) << 16); }
;   DI void operator()(const AccT& acc, const Unit& u, int wr, int wc, int fr, int fq) const {
; #pragma unroll
;     for (int ai = 0; ai < 2; ++ai)
; #pragma unroll
;       for (int m = 0; m < 4; ++m) {
;         const int row = u.pm * BM + ai * HALF + wr * 64 + m * 16 + fr;
; #pragma unroll
;         for (int bj = 0; bj < 2; ++bj) {
;           const int c8 = u.pn * BM + bj * HALF + wc * 32 + 8 * fq;
;           const bf16x8 gt = __builtin_nontemporal_load((const bf16x8*)(h + (size_t)row * NPHYS + H_GL + r * 2048 + c8));
;           bf16_t* mp = merged + (size_t)row * DM + c8;
;           f32x4 a0 = acc[ai][bj][m][0], a1 = acc[ai][bj][m][1];
; #pragma unroll
;           for (int j = 0; j < 4; ++j) { a0[j] *= bf2f((bf16_t)gt[j]); a1[j] *= bf2f((bf16_t)gt[4 + j]); }
;           if (r > 0) { const bf16x8 pv = *(const bf16x8*)mp;
; #pragma unroll
;             for (int j = 0; j < 4; ++j) { a0[j] += bf2f((bf16_t)pv[j]); a1[j] += bf2f((bf16_t)pv[4 + j]); } }
;           { u32x4 w = {cvtpk(a0[0], a0[1]), cvtpk(a0[2], a0[3]), cvtpk(a1[0], a1[1]), cvtpk(a1[2], a1[3])}; *(u32x4*)mp = w; }
;         }
;       }
;   }
.LBB0_1680:
	v_lshl_add_u32 v142, s2, 8, v148
	v_lshl_or_b32 v140, s20, 8, v150
	v_mov_b64_e32 v[144:145], s[68:69]
	v_mad_i64_i32 v[144:145], s[2:3], v142, s33, v[144:145]
	s_lshl_b32 s72, s43, 1
	v_ashrrev_i32_e32 v141, 31, v140
	v_lshl_add_u64 v[144:145], v[144:145], 0, s[72:73]
	v_lshlrev_b64 v[140:141], 1, v[140:141]
	v_lshl_add_u64 v[144:145], v[144:145], 0, v[140:141]
	v_add_co_u32_e32 v152, vcc, s82, v144
	v_ashrrev_i32_e32 v143, 31, v142
	s_nop 0
	v_addc_co_u32_e32 v153, vcc, 0, v145, vcc
	v_mov_b32_e32 v210, v152
	v_mov_b32_e32 v211, v153
	global_load_dwordx4 v[158:161], v[210:211], off nt
	global_load_dwordx4 v[162:165], v[210:211], off offset:256 nt
	s_mov_b64 s[2:3], 0x70000
	v_lshl_add_u64 v[210:211], v[210:211], 0, s[2:3]
	global_load_dwordx4 v[166:169], v[210:211], off nt
	global_load_dwordx4 v[170:173], v[210:211], off offset:256 nt
	s_mov_b64 s[2:3], 0x70000
	v_lshl_add_u64 v[210:211], v[210:211], 0, s[2:3]
	global_load_dwordx4 v[174:177], v[210:211], off nt
	global_load_dwordx4 v[178:181], v[210:211], off offset:256 nt
	s_mov_b64 s[2:3], 0x70000
	v_lshl_add_u64 v[210:211], v[210:211], 0, s[2:3]
	global_load_dwordx4 v[182:185], v[210:211], off nt
	global_load_dwordx4 v[186:189], v[210:211], off offset:256 nt
	s_mov_b64 s[2:3], 0x230000
	v_lshl_add_u64 v[210:211], v[210:211], 0, s[2:3]
	global_load_dwordx4 v[190:193], v[210:211], off nt
	global_load_dwordx4 v[194:197], v[210:211], off offset:256 nt
	s_mov_b64 s[2:3], 0x70000
	v_lshl_add_u64 v[210:211], v[210:211], 0, s[2:3]
	global_load_dwordx4 v[198:201], v[210:211], off nt
	global_load_dwordx4 v[202:205], v[210:211], off offset:256 nt
	s_mov_b64 s[2:3], 0x70000
	v_lshl_add_u64 v[210:211], v[210:211], 0, s[2:3]
	global_load_dwordx4 v[206:209], v[210:211], off nt
	global_load_dwordx4 v[214:217], v[210:211], off offset:256 nt
	s_mov_b64 s[2:3], 0x70000
	v_lshl_add_u64 v[210:211], v[210:211], 0, s[2:3]
	global_load_dwordx4 v[224:227], v[210:211], off nt
	global_load_dwordx4 v[232:235], v[210:211], off offset:256 nt
	s_waitcnt vmcnt(0)
	v_mov_b32_e32 v152, v158
	v_mov_b32_e32 v153, v159
	v_mov_b32_e32 v154, v160
	v_mov_b32_e32 v155, v161
	v_lshlrev_b64 v[146:147], 12, v[142:143]
	v_lshl_add_u64 v[156:157], s[70:71], 0, v[146:147]
	v_cndmask_b32_e64 v143, 0, 1, s[4:5]
	v_cmp_ne_u32_e64 s[2:3], 1, v143
	s_andn2_b64 vcc, exec, s[4:5]
	s_waitcnt vmcnt(0)
	v_and_b32_e32 v147, 0xffff0000, v152
	v_lshlrev_b32_e32 v146, 16, v152
	v_pk_mul_f32 v[126:127], v[126:127], v[146:147]
	v_and_b32_e32 v147, 0xffff0000, v154
	v_lshlrev_b32_e32 v146, 16, v154
	v_pk_mul_f32 v[146:147], v[122:123], v[146:147]
	v_and_b32_e32 v123, 0xffff0000, v153
	v_lshlrev_b32_e32 v122, 16, v153
	v_pk_mul_f32 v[128:129], v[128:129], v[122:123]
	v_and_b32_e32 v123, 0xffff0000, v155
	v_lshlrev_b32_e32 v122, 16, v155
	v_pk_mul_f32 v[124:125], v[124:125], v[122:123]
	v_lshl_add_u64 v[122:123], v[156:157], 0, v[140:141]
	s_cbranch_vccnz .LBB0_1682
	global_load_dwordx4 v[152:155], v[122:123], off
	s_waitcnt vmcnt(0)
	v_and_b32_e32 v157, 0xffff0000, v152
	v_lshlrev_b32_e32 v156, 16, v152
	v_pk_add_f32 v[126:127], v[126:127], v[156:157]
	v_and_b32_e32 v157, 0xffff0000, v154
	v_lshlrev_b32_e32 v156, 16, v154
	v_pk_add_f32 v[146:147], v[146:147], v[156:157]
	v_and_b32_e32 v157, 0xffff0000, v153
	v_lshlrev_b32_e32 v156, 16, v153
	v_and_b32_e32 v153, 0xffff0000, v155
	v_lshlrev_b32_e32 v152, 16, v155
	v_pk_add_f32 v[128:129], v[128:129], v[156:157]
	v_pk_add_f32 v[124:125], v[124:125], v[152:153]
.LBB0_1682:
	v_lshl_add_u64 v[144:145], v[144:145], 0, s[76:77]
	v_cvt_pk_bf16_f32 v126, v126, v127
	v_cvt_pk_bf16_f32 v127, v128, v129
	v_cvt_pk_bf16_f32 v128, v146, v147
	v_cvt_pk_bf16_f32 v129, v124, v125
	v_mov_b32_e32 v144, v162
	v_mov_b32_e32 v145, v163
	v_mov_b32_e32 v146, v164
	v_mov_b32_e32 v147, v165
	s_and_b64 vcc, exec, s[2:3]
	global_store_dwordx4 v[122:123], v[126:129], off
	v_mov_b32_e32 v212, v218
	v_and_b32_e32 v125, 0xffff0000, v144
	v_lshlrev_b32_e32 v124, 16, v144
	v_and_b32_e32 v127, 0xffff0000, v146
	v_lshlrev_b32_e32 v126, 16, v146
	v_and_b32_e32 v129, 0xffff0000, v145
	v_lshlrev_b32_e32 v128, 16, v145
	v_and_b32_e32 v145, 0xffff0000, v147
	v_lshlrev_b32_e32 v144, 16, v147
	v_pk_mul_f32 v[118:119], v[118:119], v[124:125]
	v_pk_mul_f32 v[114:115], v[114:115], v[126:127]
	v_pk_mul_f32 v[120:121], v[120:121], v[128:129]
	v_pk_mul_f32 v[116:117], v[116:117], v[144:145]
	s_cbranch_vccnz .LBB0_1684
	global_load_dwordx4 v[124:127], v[122:123], off offset:256
	s_waitcnt vmcnt(0)
	v_and_b32_e32 v129, 0xffff0000, v124
	v_lshlrev_b32_e32 v128, 16, v124
	v_pk_add_f32 v[118:119], v[118:119], v[128:129]
	v_and_b32_e32 v129, 0xffff0000, v126
	v_lshlrev_b32_e32 v128, 16, v126
	v_pk_add_f32 v[114:115], v[114:115], v[128:129]
	v_and_b32_e32 v129, 0xffff0000, v125
	v_lshlrev_b32_e32 v128, 16, v125
	v_and_b32_e32 v125, 0xffff0000, v127
	v_lshlrev_b32_e32 v124, 16, v127
	v_pk_add_f32 v[120:121], v[120:121], v[128:129]
	v_pk_add_f32 v[116:117], v[116:117], v[124:125]
; DI unsigned cvtpk(float lo, float hi) { unsigned r; asm volatile("v_cvt_pk_bf16_f32 %0, %1, %2" : "=v"(r) : "v"(lo), "v"(hi)); return r; }
; DI float bf2f(bf16_t b) { return __uint_as_float(((unsigned)b) << 16); }
;   DI void operator()(const AccT& acc, const Unit& u, int wr, int wc, int fr, int fq) const {
; #pragma unroll
;     for (int ai = 0; ai < 2; ++ai)
; #pragma unroll
;       for (int m = 0; m < 4; ++m) {
;         const int row = u.pm * BM + ai * HALF + wr * 64 + m * 16 + fr;
; #pragma unroll
;         for (int bj = 0; bj < 2; ++bj) {
;           const int c8 = u.pn * BM + bj * HALF + wc * 32 + 8 * fq;
;           const bf16x8 gt = __builtin_nontemporal_load((const bf16x8*)(h + (size_t)row * NPHYS + H_GL + r * 2048 + c8));
;           bf16_t* mp = merged + (size_t)row * DM + c8;
;           f32x4 a0 = acc[ai][bj][m][0], a1 = acc[ai][bj][m][1];
; #pragma unroll
;           for (int j = 0; j < 4; ++j) { a0[j] *= bf2f((bf16_t)gt[j]); a1[j] *= bf2f((bf16_t)gt[4 + j]); }
;           if (r > 0) { const bf16x8 pv = *(const bf16x8*)mp;
; #pragma unroll
;             for (int j = 0; j < 4; ++j) { a0[j] += bf2f((bf16_t)pv[j]); a1[j] += bf2f((bf16_t)pv[4 + j]); } }
;           { u32x4 w = {cvtpk(a0[0], a0[1]), cvtpk(a0[2], a0[3]), cvtpk(a1[0], a1[1]), cvtpk(a1[2], a1[3])}; *(u32x4*)mp = w; }
;         }
;       }
;   }
.LBB0_1684:
	v_cvt_pk_bf16_f32 v118, v118, v119
	v_cvt_pk_bf16_f32 v119, v120, v121
	v_cvt_pk_bf16_f32 v120, v114, v115
	v_or_b32_e32 v114, 16, v142
	v_cvt_pk_bf16_f32 v121, v116, v117
	global_store_dwordx4 v[122:123], v[118:121], off offset:256
	v_ashrrev_i32_e32 v115, 31, v114
	v_lshlrev_b64 v[116:117], 12, v[114:115]
	v_mov_b64_e32 v[118:119], s[68:69]
	v_mad_i64_i32 v[114:115], s[22:23], v114, s33, v[118:119]
	v_lshl_add_u64 v[114:115], v[114:115], 0, s[72:73]
	v_lshl_add_u64 v[114:115], v[114:115], 0, v[140:141]
	v_add_co_u32_e32 v118, vcc, s82, v114
	v_lshl_add_u64 v[122:123], s[70:71], 0, v[116:117]
	s_nop 0
	v_addc_co_u32_e32 v119, vcc, 0, v115, vcc
	v_mov_b32_e32 v118, v166
	v_mov_b32_e32 v119, v167
	v_mov_b32_e32 v120, v168
	v_mov_b32_e32 v121, v169
	s_and_b64 vcc, exec, s[2:3]
	v_and_b32_e32 v117, 0xffff0000, v118
	v_lshlrev_b32_e32 v116, 16, v118
	v_pk_mul_f32 v[110:111], v[110:111], v[116:117]
	v_and_b32_e32 v117, 0xffff0000, v120
	v_lshlrev_b32_e32 v116, 16, v120
	v_pk_mul_f32 v[116:117], v[106:107], v[116:117]
	v_and_b32_e32 v107, 0xffff0000, v119
	v_lshlrev_b32_e32 v106, 16, v119
	v_pk_mul_f32 v[112:113], v[112:113], v[106:107]
	v_and_b32_e32 v107, 0xffff0000, v121
	v_lshlrev_b32_e32 v106, 16, v121
	v_pk_mul_f32 v[108:109], v[108:109], v[106:107]
	v_lshl_add_u64 v[106:107], v[122:123], 0, v[140:141]
	s_cbranch_vccnz .LBB0_1686
	global_load_dwordx4 v[118:121], v[106:107], off
	s_waitcnt vmcnt(0)
	v_and_b32_e32 v123, 0xffff0000, v118
	v_lshlrev_b32_e32 v122, 16, v118
	v_pk_add_f32 v[110:111], v[110:111], v[122:123]
	v_and_b32_e32 v123, 0xffff0000, v120
	v_lshlrev_b32_e32 v122, 16, v120
	v_pk_add_f32 v[116:117], v[116:117], v[122:123]
	v_and_b32_e32 v123, 0xffff0000, v119
	v_lshlrev_b32_e32 v122, 16, v119
	v_and_b32_e32 v119, 0xffff0000, v121
	v_lshlrev_b32_e32 v118, 16, v121
	v_pk_add_f32 v[112:113], v[112:113], v[122:123]
	v_pk_add_f32 v[108:109], v[108:109], v[118:119]
.LBB0_1686:
	v_lshl_add_u64 v[114:115], v[114:115], 0, s[76:77]
	v_cvt_pk_bf16_f32 v110, v110, v111
	v_cvt_pk_bf16_f32 v111, v112, v113
	v_cvt_pk_bf16_f32 v112, v116, v117
	v_cvt_pk_bf16_f32 v113, v108, v109
	v_mov_b32_e32 v114, v170
	v_mov_b32_e32 v115, v171
	v_mov_b32_e32 v116, v172
	v_mov_b32_e32 v117, v173
	s_and_b64 vcc, exec, s[2:3]
	global_store_dwordx4 v[106:107], v[110:113], off
	v_and_b32_e32 v109, 0xffff0000, v114
	v_lshlrev_b32_e32 v108, 16, v114
	v_and_b32_e32 v111, 0xffff0000, v116
	v_lshlrev_b32_e32 v110, 16, v116
	v_and_b32_e32 v113, 0xffff0000, v115
	v_lshlrev_b32_e32 v112, 16, v115
	v_and_b32_e32 v115, 0xffff0000, v117
	v_lshlrev_b32_e32 v114, 16, v117
	v_pk_mul_f32 v[102:103], v[102:103], v[108:109]
	v_pk_mul_f32 v[98:99], v[98:99], v[110:111]
	v_pk_mul_f32 v[104:105], v[104:105], v[112:113]
	v_pk_mul_f32 v[100:101], v[100:101], v[114:115]
	s_cbranch_vccnz .LBB0_1688
	global_load_dwordx4 v[108:111], v[106:107], off offset:256
	s_waitcnt vmcnt(0)
	v_and_b32_e32 v113, 0xffff0000, v108
	v_lshlrev_b32_e32 v112, 16, v108
	v_pk_add_f32 v[102:103], v[102:103], v[112:113]
	v_and_b32_e32 v113, 0xffff0000, v110
	v_lshlrev_b32_e32 v112, 16, v110
	v_pk_add_f32 v[98:99], v[98:99], v[112:113]
	v_and_b32_e32 v113, 0xffff0000, v109
	v_lshlrev_b32_e32 v112, 16, v109
	v_and_b32_e32 v109, 0xffff0000, v111
	v_lshlrev_b32_e32 v108, 16, v111
	v_pk_add_f32 v[104:105], v[104:105], v[112:113]
	v_pk_add_f32 v[100:101], v[100:101], v[108:109]
.LBB0_1688:
	v_cvt_pk_bf16_f32 v102, v102, v103
	v_cvt_pk_bf16_f32 v103, v104, v105
	v_cvt_pk_bf16_f32 v104, v98, v99
	v_or_b32_e32 v98, 32, v142
	v_cvt_pk_bf16_f32 v105, v100, v101
	global_store_dwordx4 v[106:107], v[102:105], off offset:256
	v_ashrrev_i32_e32 v99, 31, v98
	v_lshlrev_b64 v[100:101], 12, v[98:99]
	v_mov_b64_e32 v[102:103], s[68:69]
	v_mad_i64_i32 v[98:99], s[22:23], v98, s33, v[102:103]
	v_lshl_add_u64 v[98:99], v[98:99], 0, s[72:73]
	v_lshl_add_u64 v[98:99], v[98:99], 0, v[140:141]
	v_add_co_u32_e32 v102, vcc, s82, v98
	v_lshl_add_u64 v[106:107], s[70:71], 0, v[100:101]
	s_nop 0
	v_addc_co_u32_e32 v103, vcc, 0, v99, vcc
	v_mov_b32_e32 v102, v174
	v_mov_b32_e32 v103, v175
	v_mov_b32_e32 v104, v176
	v_mov_b32_e32 v105, v177
	s_and_b64 vcc, exec, s[2:3]
	v_and_b32_e32 v101, 0xffff0000, v102
	v_lshlrev_b32_e32 v100, 16, v102
	v_pk_mul_f32 v[94:95], v[94:95], v[100:101]
	v_and_b32_e32 v101, 0xffff0000, v104
	v_lshlrev_b32_e32 v100, 16, v104
	v_pk_mul_f32 v[100:101], v[90:91], v[100:101]
	v_and_b32_e32 v91, 0xffff0000, v103
	v_lshlrev_b32_e32 v90, 16, v103
	v_pk_mul_f32 v[96:97], v[96:97], v[90:91]
	v_and_b32_e32 v91, 0xffff0000, v105
	v_lshlrev_b32_e32 v90, 16, v105
	v_pk_mul_f32 v[92:93], v[92:93], v[90:91]
	v_lshl_add_u64 v[90:91], v[106:107], 0, v[140:141]
	s_cbranch_vccnz .LBB0_1690
	global_load_dwordx4 v[102:105], v[90:91], off
	s_waitcnt vmcnt(0)
	v_and_b32_e32 v107, 0xffff0000, v102
	v_lshlrev_b32_e32 v106, 16, v102
	v_pk_add_f32 v[94:95], v[94:95], v[106:107]
	v_and_b32_e32 v107, 0xffff0000, v104
	v_lshlrev_b32_e32 v106, 16, v104
	v_pk_add_f32 v[100:101], v[100:101], v[106:107]
	v_and_b32_e32 v107, 0xffff0000, v103
	v_lshlrev_b32_e32 v106, 16, v103
	v_and_b32_e32 v103, 0xffff0000, v105
	v_lshlrev_b32_e32 v102, 16, v105
	v_pk_add_f32 v[96:97], v[96:97], v[106:107]
	v_pk_add_f32 v[92:93], v[92:93], v[102:103]
; DI unsigned cvtpk(float lo, float hi) { unsigned r; asm volatile("v_cvt_pk_bf16_f32 %0, %1, %2" : "=v"(r) : "v"(lo), "v"(hi)); return r; }
; DI float bf2f(bf16_t b) { return __uint_as_float(((unsigned)b) << 16); }
;   DI void operator()(const AccT& acc, const Unit& u, int wr, int wc, int fr, int fq) const {
; #pragma unroll
;     for (int ai = 0; ai < 2; ++ai)
; #pragma unroll
;       for (int m = 0; m < 4; ++m) {
;         const int row = u.pm * BM + ai * HALF + wr * 64 + m * 16 + fr;
; #pragma unroll
;         for (int bj = 0; bj < 2; ++bj) {
;           const int c8 = u.pn * BM + bj * HALF + wc * 32 + 8 * fq;
;           const bf16x8 gt = __builtin_nontemporal_load((const bf16x8*)(h + (size_t)row * NPHYS + H_GL + r * 2048 + c8));
;           bf16_t* mp = merged + (size_t)row * DM + c8;
;           f32x4 a0 = acc[ai][bj][m][0], a1 = acc[ai][bj][m][1];
; #pragma unroll
;           for (int j = 0; j < 4; ++j) { a0[j] *= bf2f((bf16_t)gt[j]); a1[j] *= bf2f((bf16_t)gt[4 + j]); }
;           if (r > 0) { const bf16x8 pv = *(const bf16x8*)mp;
; #pragma unroll
;             for (int j = 0; j < 4; ++j) { a0[j] += bf2f((bf16_t)pv[j]); a1[j] += bf2f((bf16_t)pv[4 + j]); } }
;           { u32x4 w = {cvtpk(a0[0], a0[1]), cvtpk(a0[2], a0[3]), cvtpk(a1[0], a1[1]), cvtpk(a1[2], a1[3])}; *(u32x4*)mp = w; }
;         }
;       }
;   }
.LBB0_1690:
	v_lshl_add_u64 v[98:99], v[98:99], 0, s[76:77]
	v_cvt_pk_bf16_f32 v94, v94, v95
	v_cvt_pk_bf16_f32 v95, v96, v97
	v_cvt_pk_bf16_f32 v96, v100, v101
	v_cvt_pk_bf16_f32 v97, v92, v93
	v_mov_b32_e32 v98, v178
	v_mov_b32_e32 v99, v179
	v_mov_b32_e32 v100, v180
	v_mov_b32_e32 v101, v181
	s_and_b64 vcc, exec, s[2:3]
	global_store_dwordx4 v[90:91], v[94:97], off
	v_and_b32_e32 v93, 0xffff0000, v98
	v_lshlrev_b32_e32 v92, 16, v98
	v_and_b32_e32 v95, 0xffff0000, v100
	v_lshlrev_b32_e32 v94, 16, v100
	v_and_b32_e32 v97, 0xffff0000, v99
	v_lshlrev_b32_e32 v96, 16, v99
	v_and_b32_e32 v99, 0xffff0000, v101
	v_lshlrev_b32_e32 v98, 16, v101
	v_pk_mul_f32 v[86:87], v[86:87], v[92:93]
	v_pk_mul_f32 v[82:83], v[82:83], v[94:95]
	v_pk_mul_f32 v[88:89], v[88:89], v[96:97]
	v_pk_mul_f32 v[84:85], v[84:85], v[98:99]
	s_cbranch_vccnz .LBB0_1692
	global_load_dwordx4 v[92:95], v[90:91], off offset:256
	s_waitcnt vmcnt(0)
	v_and_b32_e32 v97, 0xffff0000, v92
	v_lshlrev_b32_e32 v96, 16, v92
	v_pk_add_f32 v[86:87], v[86:87], v[96:97]
	v_and_b32_e32 v97, 0xffff0000, v94
	v_lshlrev_b32_e32 v96, 16, v94
	v_pk_add_f32 v[82:83], v[82:83], v[96:97]
	v_and_b32_e32 v97, 0xffff0000, v93
	v_lshlrev_b32_e32 v96, 16, v93
	v_and_b32_e32 v93, 0xffff0000, v95
	v_lshlrev_b32_e32 v92, 16, v95
	v_pk_add_f32 v[88:89], v[88:89], v[96:97]
	v_pk_add_f32 v[84:85], v[84:85], v[92:93]
.LBB0_1692:
	v_cvt_pk_bf16_f32 v86, v86, v87
	v_cvt_pk_bf16_f32 v87, v88, v89
	v_cvt_pk_bf16_f32 v88, v82, v83
	v_or_b32_e32 v82, 48, v142
	v_cvt_pk_bf16_f32 v89, v84, v85
	global_store_dwordx4 v[90:91], v[86:89], off offset:256
	v_ashrrev_i32_e32 v83, 31, v82
	v_lshlrev_b64 v[84:85], 12, v[82:83]
	v_mov_b64_e32 v[86:87], s[68:69]
	v_mad_i64_i32 v[82:83], s[22:23], v82, s33, v[86:87]
	v_lshl_add_u64 v[82:83], v[82:83], 0, s[72:73]
	v_lshl_add_u64 v[82:83], v[82:83], 0, v[140:141]
	v_add_co_u32_e32 v86, vcc, s82, v82
	v_lshl_add_u64 v[90:91], s[70:71], 0, v[84:85]
	s_nop 0
	v_addc_co_u32_e32 v87, vcc, 0, v83, vcc
	v_mov_b32_e32 v86, v182
	v_mov_b32_e32 v87, v183
	v_mov_b32_e32 v88, v184
	v_mov_b32_e32 v89, v185
	s_and_b64 vcc, exec, s[2:3]
	v_and_b32_e32 v85, 0xffff0000, v86
	v_lshlrev_b32_e32 v84, 16, v86
	v_pk_mul_f32 v[78:79], v[78:79], v[84:85]
	v_and_b32_e32 v85, 0xffff0000, v88
	v_lshlrev_b32_e32 v84, 16, v88
	v_pk_mul_f32 v[84:85], v[74:75], v[84:85]
	v_and_b32_e32 v75, 0xffff0000, v87
	v_lshlrev_b32_e32 v74, 16, v87
	v_pk_mul_f32 v[80:81], v[80:81], v[74:75]
	v_and_b32_e32 v75, 0xffff0000, v89
	v_lshlrev_b32_e32 v74, 16, v89
	v_pk_mul_f32 v[76:77], v[76:77], v[74:75]
	v_lshl_add_u64 v[74:75], v[90:91], 0, v[140:141]
	s_cbranch_vccnz .LBB0_1694
	global_load_dwordx4 v[86:89], v[74:75], off
	s_waitcnt vmcnt(0)
	v_and_b32_e32 v91, 0xffff0000, v86
	v_lshlrev_b32_e32 v90, 16, v86
	v_pk_add_f32 v[78:79], v[78:79], v[90:91]
	v_and_b32_e32 v91, 0xffff0000, v88
	v_lshlrev_b32_e32 v90, 16, v88
	v_pk_add_f32 v[84:85], v[84:85], v[90:91]
	v_and_b32_e32 v91, 0xffff0000, v87
	v_lshlrev_b32_e32 v90, 16, v87
	v_and_b32_e32 v87, 0xffff0000, v89
	v_lshlrev_b32_e32 v86, 16, v89
	v_pk_add_f32 v[80:81], v[80:81], v[90:91]
	v_pk_add_f32 v[76:77], v[76:77], v[86:87]
.LBB0_1694:
	v_lshl_add_u64 v[82:83], v[82:83], 0, s[76:77]
	v_cvt_pk_bf16_f32 v78, v78, v79
	v_cvt_pk_bf16_f32 v79, v80, v81
	v_cvt_pk_bf16_f32 v80, v84, v85
	v_cvt_pk_bf16_f32 v81, v76, v77
	v_mov_b32_e32 v82, v186
	v_mov_b32_e32 v83, v187
	v_mov_b32_e32 v84, v188
	v_mov_b32_e32 v85, v189
	s_and_b64 vcc, exec, s[2:3]
	global_store_dwordx4 v[74:75], v[78:81], off
	v_and_b32_e32 v77, 0xffff0000, v82
	v_lshlrev_b32_e32 v76, 16, v82
	v_and_b32_e32 v79, 0xffff0000, v84
	v_lshlrev_b32_e32 v78, 16, v84
	v_and_b32_e32 v81, 0xffff0000, v83
	v_lshlrev_b32_e32 v80, 16, v83
	v_and_b32_e32 v83, 0xffff0000, v85
	v_lshlrev_b32_e32 v82, 16, v85
	v_pk_mul_f32 v[70:71], v[70:71], v[76:77]
	v_pk_mul_f32 v[66:67], v[66:67], v[78:79]
	v_pk_mul_f32 v[72:73], v[72:73], v[80:81]
	v_pk_mul_f32 v[68:69], v[68:69], v[82:83]
	s_cbranch_vccnz .LBB0_1696
	global_load_dwordx4 v[76:79], v[74:75], off offset:256
	s_waitcnt vmcnt(0)
	v_and_b32_e32 v81, 0xffff0000, v76
	v_lshlrev_b32_e32 v80, 16, v76
	v_pk_add_f32 v[70:71], v[70:71], v[80:81]
	v_and_b32_e32 v81, 0xffff0000, v78
	v_lshlrev_b32_e32 v80, 16, v78
	v_pk_add_f32 v[66:67], v[66:67], v[80:81]
	v_and_b32_e32 v81, 0xffff0000, v77
	v_lshlrev_b32_e32 v80, 16, v77
	v_and_b32_e32 v77, 0xffff0000, v79
	v_lshlrev_b32_e32 v76, 16, v79
	v_pk_add_f32 v[72:73], v[72:73], v[80:81]
	v_pk_add_f32 v[68:69], v[68:69], v[76:77]
.LBB0_1696:
	v_cvt_pk_bf16_f32 v70, v70, v71
	v_cvt_pk_bf16_f32 v71, v72, v73
	v_cvt_pk_bf16_f32 v72, v66, v67
	v_add_u32_e32 v66, 0x80, v142
	v_cvt_pk_bf16_f32 v73, v68, v69
	global_store_dwordx4 v[74:75], v[70:73], off offset:256
	v_ashrrev_i32_e32 v67, 31, v66
	v_lshlrev_b64 v[68:69], 12, v[66:67]
	v_mov_b64_e32 v[70:71], s[68:69]
	v_mad_i64_i32 v[66:67], s[22:23], v66, s33, v[70:71]
	v_lshl_add_u64 v[66:67], v[66:67], 0, s[72:73]
	v_lshl_add_u64 v[66:67], v[66:67], 0, v[140:141]
	v_add_co_u32_e32 v70, vcc, s82, v66
	v_lshl_add_u64 v[74:75], s[70:71], 0, v[68:69]
	s_nop 0
	v_addc_co_u32_e32 v71, vcc, 0, v67, vcc
	v_mov_b32_e32 v70, v190
	v_mov_b32_e32 v71, v191
	v_mov_b32_e32 v72, v192
	v_mov_b32_e32 v73, v193
	s_and_b64 vcc, exec, s[2:3]
	v_and_b32_e32 v69, 0xffff0000, v70
	v_lshlrev_b32_e32 v68, 16, v70
	v_pk_mul_f32 v[62:63], v[62:63], v[68:69]
	v_and_b32_e32 v69, 0xffff0000, v72
	v_lshlrev_b32_e32 v68, 16, v72
	v_pk_mul_f32 v[68:69], v[58:59], v[68:69]
	v_and_b32_e32 v59, 0xffff0000, v71
	v_lshlrev_b32_e32 v58, 16, v71
	v_pk_mul_f32 v[64:65], v[64:65], v[58:59]
	v_and_b32_e32 v59, 0xffff0000, v73
	v_lshlrev_b32_e32 v58, 16, v73
	v_pk_mul_f32 v[60:61], v[60:61], v[58:59]
	v_lshl_add_u64 v[58:59], v[74:75], 0, v[140:141]
	s_cbranch_vccnz .LBB0_1698
	global_load_dwordx4 v[70:73], v[58:59], off
	s_waitcnt vmcnt(0)
	v_and_b32_e32 v75, 0xffff0000, v70
	v_lshlrev_b32_e32 v74, 16, v70
	v_pk_add_f32 v[62:63], v[62:63], v[74:75]
	v_and_b32_e32 v75, 0xffff0000, v72
	v_lshlrev_b32_e32 v74, 16, v72
	v_pk_add_f32 v[68:69], v[68:69], v[74:75]
	v_and_b32_e32 v75, 0xffff0000, v71
	v_lshlrev_b32_e32 v74, 16, v71
	v_and_b32_e32 v71, 0xffff0000, v73
	v_lshlrev_b32_e32 v70, 16, v73
	v_pk_add_f32 v[64:65], v[64:65], v[74:75]
	v_pk_add_f32 v[60:61], v[60:61], v[70:71]
; DI unsigned cvtpk(float lo, float hi) { unsigned r; asm volatile("v_cvt_pk_bf16_f32 %0, %1, %2" : "=v"(r) : "v"(lo), "v"(hi)); return r; }
; DI float bf2f(bf16_t b) { return __uint_as_float(((unsigned)b) << 16); }
;   DI void operator()(const AccT& acc, const Unit& u, int wr, int wc, int fr, int fq) const {
; #pragma unroll
;     for (int ai = 0; ai < 2; ++ai)
; #pragma unroll
;       for (int m = 0; m < 4; ++m) {
;         const int row = u.pm * BM + ai * HALF + wr * 64 + m * 16 + fr;
; #pragma unroll
;         for (int bj = 0; bj < 2; ++bj) {
;           const int c8 = u.pn * BM + bj * HALF + wc * 32 + 8 * fq;
;           const bf16x8 gt = __builtin_nontemporal_load((const bf16x8*)(h + (size_t)row * NPHYS + H_GL + r * 2048 + c8));
;           bf16_t* mp = merged + (size_t)row * DM + c8;
;           f32x4 a0 = acc[ai][bj][m][0], a1 = acc[ai][bj][m][1];
; #pragma unroll
;           for (int j = 0; j < 4; ++j) { a0[j] *= bf2f((bf16_t)gt[j]); a1[j] *= bf2f((bf16_t)gt[4 + j]); }
;           if (r > 0) { const bf16x8 pv = *(const bf16x8*)mp;
; #pragma unroll
;             for (int j = 0; j < 4; ++j) { a0[j] += bf2f((bf16_t)pv[j]); a1[j] += bf2f((bf16_t)pv[4 + j]); } }
;           { u32x4 w = {cvtpk(a0[0], a0[1]), cvtpk(a0[2], a0[3]), cvtpk(a1[0], a1[1]), cvtpk(a1[2], a1[3])}; *(u32x4*)mp = w; }
;         }
;       }
;   }
.LBB0_1698:
	v_lshl_add_u64 v[66:67], v[66:67], 0, s[76:77]
	v_cvt_pk_bf16_f32 v62, v62, v63
	v_cvt_pk_bf16_f32 v63, v64, v65
	v_cvt_pk_bf16_f32 v64, v68, v69
	v_cvt_pk_bf16_f32 v65, v60, v61
	v_mov_b32_e32 v66, v194
	v_mov_b32_e32 v67, v195
	v_mov_b32_e32 v68, v196
	v_mov_b32_e32 v69, v197
	s_and_b64 vcc, exec, s[2:3]
	global_store_dwordx4 v[58:59], v[62:65], off
	v_and_b32_e32 v61, 0xffff0000, v66
	v_lshlrev_b32_e32 v60, 16, v66
	v_and_b32_e32 v63, 0xffff0000, v68
	v_lshlrev_b32_e32 v62, 16, v68
	v_and_b32_e32 v65, 0xffff0000, v67
	v_lshlrev_b32_e32 v64, 16, v67
	v_and_b32_e32 v67, 0xffff0000, v69
	v_lshlrev_b32_e32 v66, 16, v69
	v_pk_mul_f32 v[54:55], v[54:55], v[60:61]
	v_pk_mul_f32 v[50:51], v[50:51], v[62:63]
	v_pk_mul_f32 v[56:57], v[56:57], v[64:65]
	v_pk_mul_f32 v[52:53], v[52:53], v[66:67]
	s_cbranch_vccnz .LBB0_1700
	global_load_dwordx4 v[60:63], v[58:59], off offset:256
	s_waitcnt vmcnt(0)
	v_and_b32_e32 v65, 0xffff0000, v60
	v_lshlrev_b32_e32 v64, 16, v60
	v_pk_add_f32 v[54:55], v[54:55], v[64:65]
	v_and_b32_e32 v65, 0xffff0000, v62
	v_lshlrev_b32_e32 v64, 16, v62
	v_pk_add_f32 v[50:51], v[50:51], v[64:65]
	v_and_b32_e32 v65, 0xffff0000, v61
	v_lshlrev_b32_e32 v64, 16, v61
	v_and_b32_e32 v61, 0xffff0000, v63
	v_lshlrev_b32_e32 v60, 16, v63
	v_pk_add_f32 v[56:57], v[56:57], v[64:65]
	v_pk_add_f32 v[52:53], v[52:53], v[60:61]
.LBB0_1700:
	v_cvt_pk_bf16_f32 v54, v54, v55
	v_cvt_pk_bf16_f32 v55, v56, v57
	v_cvt_pk_bf16_f32 v56, v50, v51
	v_add_u32_e32 v50, 0x90, v142
	v_cvt_pk_bf16_f32 v57, v52, v53
	global_store_dwordx4 v[58:59], v[54:57], off offset:256
	v_ashrrev_i32_e32 v51, 31, v50
	v_lshlrev_b64 v[52:53], 12, v[50:51]
	v_mov_b64_e32 v[54:55], s[68:69]
	v_mad_i64_i32 v[50:51], s[22:23], v50, s33, v[54:55]
	v_lshl_add_u64 v[50:51], v[50:51], 0, s[72:73]
	v_lshl_add_u64 v[50:51], v[50:51], 0, v[140:141]
	v_add_co_u32_e32 v54, vcc, s82, v50
	v_lshl_add_u64 v[58:59], s[70:71], 0, v[52:53]
	s_nop 0
	v_addc_co_u32_e32 v55, vcc, 0, v51, vcc
	v_mov_b32_e32 v54, v198
	v_mov_b32_e32 v55, v199
	v_mov_b32_e32 v56, v200
	v_mov_b32_e32 v57, v201
	s_and_b64 vcc, exec, s[2:3]
	v_and_b32_e32 v53, 0xffff0000, v54
	v_lshlrev_b32_e32 v52, 16, v54
	v_pk_mul_f32 v[46:47], v[46:47], v[52:53]
	v_and_b32_e32 v53, 0xffff0000, v56
	v_lshlrev_b32_e32 v52, 16, v56
	v_pk_mul_f32 v[52:53], v[42:43], v[52:53]
	v_and_b32_e32 v43, 0xffff0000, v55
	v_lshlrev_b32_e32 v42, 16, v55
	v_pk_mul_f32 v[48:49], v[48:49], v[42:43]
	v_and_b32_e32 v43, 0xffff0000, v57
	v_lshlrev_b32_e32 v42, 16, v57
	v_pk_mul_f32 v[44:45], v[44:45], v[42:43]
	v_lshl_add_u64 v[42:43], v[58:59], 0, v[140:141]
	s_cbranch_vccnz .LBB0_1702
	global_load_dwordx4 v[54:57], v[42:43], off
	s_waitcnt vmcnt(0)
	v_and_b32_e32 v59, 0xffff0000, v54
	v_lshlrev_b32_e32 v58, 16, v54
	v_pk_add_f32 v[46:47], v[46:47], v[58:59]
	v_and_b32_e32 v59, 0xffff0000, v56
	v_lshlrev_b32_e32 v58, 16, v56
	v_pk_add_f32 v[52:53], v[52:53], v[58:59]
	v_and_b32_e32 v59, 0xffff0000, v55
	v_lshlrev_b32_e32 v58, 16, v55
	v_and_b32_e32 v55, 0xffff0000, v57
	v_lshlrev_b32_e32 v54, 16, v57
	v_pk_add_f32 v[48:49], v[48:49], v[58:59]
	v_pk_add_f32 v[44:45], v[44:45], v[54:55]
.LBB0_1702:
	v_lshl_add_u64 v[50:51], v[50:51], 0, s[76:77]
	v_cvt_pk_bf16_f32 v46, v46, v47
	v_cvt_pk_bf16_f32 v47, v48, v49
	v_cvt_pk_bf16_f32 v48, v52, v53
	v_cvt_pk_bf16_f32 v49, v44, v45
	v_mov_b32_e32 v50, v202
	v_mov_b32_e32 v51, v203
	v_mov_b32_e32 v52, v204
	v_mov_b32_e32 v53, v205
	s_and_b64 vcc, exec, s[2:3]
	global_store_dwordx4 v[42:43], v[46:49], off
	v_and_b32_e32 v45, 0xffff0000, v50
	v_lshlrev_b32_e32 v44, 16, v50
	v_and_b32_e32 v47, 0xffff0000, v52
	v_lshlrev_b32_e32 v46, 16, v52
	v_and_b32_e32 v49, 0xffff0000, v51
	v_lshlrev_b32_e32 v48, 16, v51
	v_and_b32_e32 v51, 0xffff0000, v53
	v_lshlrev_b32_e32 v50, 16, v53
	v_pk_mul_f32 v[38:39], v[38:39], v[44:45]
	v_pk_mul_f32 v[34:35], v[34:35], v[46:47]
	v_pk_mul_f32 v[40:41], v[40:41], v[48:49]
	v_pk_mul_f32 v[36:37], v[36:37], v[50:51]
	s_cbranch_vccnz .LBB0_1704
	global_load_dwordx4 v[44:47], v[42:43], off offset:256
	s_waitcnt vmcnt(0)
	v_and_b32_e32 v49, 0xffff0000, v44
	v_lshlrev_b32_e32 v48, 16, v44
	v_pk_add_f32 v[38:39], v[38:39], v[48:49]
	v_and_b32_e32 v49, 0xffff0000, v46
	v_lshlrev_b32_e32 v48, 16, v46
	v_pk_add_f32 v[34:35], v[34:35], v[48:49]
	v_and_b32_e32 v49, 0xffff0000, v45
	v_lshlrev_b32_e32 v48, 16, v45
	v_and_b32_e32 v45, 0xffff0000, v47
	v_lshlrev_b32_e32 v44, 16, v47
	v_pk_add_f32 v[40:41], v[40:41], v[48:49]
	v_pk_add_f32 v[36:37], v[36:37], v[44:45]
; DI unsigned cvtpk(float lo, float hi) { unsigned r; asm volatile("v_cvt_pk_bf16_f32 %0, %1, %2" : "=v"(r) : "v"(lo), "v"(hi)); return r; }
; DI float bf2f(bf16_t b) { return __uint_as_float(((unsigned)b) << 16); }
;   DI void operator()(const AccT& acc, const Unit& u, int wr, int wc, int fr, int fq) const {
; #pragma unroll
;     for (int ai = 0; ai < 2; ++ai)
; #pragma unroll
;       for (int m = 0; m < 4; ++m) {
;         const int row = u.pm * BM + ai * HALF + wr * 64 + m * 16 + fr;
; #pragma unroll
;         for (int bj = 0; bj < 2; ++bj) {
;           const int c8 = u.pn * BM + bj * HALF + wc * 32 + 8 * fq;
;           const bf16x8 gt = __builtin_nontemporal_load((const bf16x8*)(h + (size_t)row * NPHYS + H_GL + r * 2048 + c8));
;           bf16_t* mp = merged + (size_t)row * DM + c8;
;           f32x4 a0 = acc[ai][bj][m][0], a1 = acc[ai][bj][m][1];
; #pragma unroll
;           for (int j = 0; j < 4; ++j) { a0[j] *= bf2f((bf16_t)gt[j]); a1[j] *= bf2f((bf16_t)gt[4 + j]); }
;           if (r > 0) { const bf16x8 pv = *(const bf16x8*)mp;
; #pragma unroll
;             for (int j = 0; j < 4; ++j) { a0[j] += bf2f((bf16_t)pv[j]); a1[j] += bf2f((bf16_t)pv[4 + j]); } }
;           { u32x4 w = {cvtpk(a0[0], a0[1]), cvtpk(a0[2], a0[3]), cvtpk(a1[0], a1[1]), cvtpk(a1[2], a1[3])}; *(u32x4*)mp = w; }
;         }
;       }
;   }
.LBB0_1704:
	v_cvt_pk_bf16_f32 v38, v38, v39
	v_cvt_pk_bf16_f32 v39, v40, v41
	v_cvt_pk_bf16_f32 v40, v34, v35
	v_add_u32_e32 v34, 0xa0, v142
	v_cvt_pk_bf16_f32 v41, v36, v37
	global_store_dwordx4 v[42:43], v[38:41], off offset:256
	v_ashrrev_i32_e32 v35, 31, v34
	v_lshlrev_b64 v[36:37], 12, v[34:35]
	v_mov_b64_e32 v[38:39], s[68:69]
	v_mad_i64_i32 v[34:35], s[22:23], v34, s33, v[38:39]
	v_lshl_add_u64 v[34:35], v[34:35], 0, s[72:73]
	v_lshl_add_u64 v[34:35], v[34:35], 0, v[140:141]
	v_add_co_u32_e32 v38, vcc, s82, v34
	v_lshl_add_u64 v[42:43], s[70:71], 0, v[36:37]
	s_nop 0
	v_addc_co_u32_e32 v39, vcc, 0, v35, vcc
	v_mov_b32_e32 v38, v206
	v_mov_b32_e32 v39, v207
	v_mov_b32_e32 v40, v208
	v_mov_b32_e32 v41, v209
	s_and_b64 vcc, exec, s[2:3]
	v_and_b32_e32 v37, 0xffff0000, v38
	v_lshlrev_b32_e32 v36, 16, v38
	v_pk_mul_f32 v[30:31], v[30:31], v[36:37]
	v_and_b32_e32 v37, 0xffff0000, v40
	v_lshlrev_b32_e32 v36, 16, v40
	v_pk_mul_f32 v[36:37], v[26:27], v[36:37]
	v_and_b32_e32 v27, 0xffff0000, v39
	v_lshlrev_b32_e32 v26, 16, v39
	v_pk_mul_f32 v[32:33], v[32:33], v[26:27]
	v_and_b32_e32 v27, 0xffff0000, v41
	v_lshlrev_b32_e32 v26, 16, v41
	v_pk_mul_f32 v[28:29], v[28:29], v[26:27]
	v_lshl_add_u64 v[26:27], v[42:43], 0, v[140:141]
	s_cbranch_vccnz .LBB0_1706
	global_load_dwordx4 v[38:41], v[26:27], off
	s_waitcnt vmcnt(0)
	v_and_b32_e32 v43, 0xffff0000, v38
	v_lshlrev_b32_e32 v42, 16, v38
	v_pk_add_f32 v[30:31], v[30:31], v[42:43]
	v_and_b32_e32 v43, 0xffff0000, v40
	v_lshlrev_b32_e32 v42, 16, v40
	v_pk_add_f32 v[36:37], v[36:37], v[42:43]
	v_and_b32_e32 v43, 0xffff0000, v39
	v_lshlrev_b32_e32 v42, 16, v39
	v_and_b32_e32 v39, 0xffff0000, v41
	v_lshlrev_b32_e32 v38, 16, v41
	v_pk_add_f32 v[32:33], v[32:33], v[42:43]
	v_pk_add_f32 v[28:29], v[28:29], v[38:39]
.LBB0_1706:
	v_lshl_add_u64 v[34:35], v[34:35], 0, s[76:77]
	v_cvt_pk_bf16_f32 v30, v30, v31
	v_cvt_pk_bf16_f32 v31, v32, v33
	v_cvt_pk_bf16_f32 v32, v36, v37
	v_cvt_pk_bf16_f32 v33, v28, v29
	v_mov_b32_e32 v34, v214
	v_mov_b32_e32 v35, v215
	v_mov_b32_e32 v36, v216
	v_mov_b32_e32 v37, v217
	s_and_b64 vcc, exec, s[2:3]
	global_store_dwordx4 v[26:27], v[30:33], off
	v_and_b32_e32 v29, 0xffff0000, v34
	v_lshlrev_b32_e32 v28, 16, v34
	v_and_b32_e32 v31, 0xffff0000, v36
	v_lshlrev_b32_e32 v30, 16, v36
	v_and_b32_e32 v33, 0xffff0000, v35
	v_lshlrev_b32_e32 v32, 16, v35
	v_and_b32_e32 v35, 0xffff0000, v37
	v_lshlrev_b32_e32 v34, 16, v37
	v_pk_mul_f32 v[22:23], v[22:23], v[28:29]
	v_pk_mul_f32 v[18:19], v[18:19], v[30:31]
	v_pk_mul_f32 v[24:25], v[24:25], v[32:33]
	v_pk_mul_f32 v[20:21], v[20:21], v[34:35]
	s_cbranch_vccnz .LBB0_1708
	global_load_dwordx4 v[28:31], v[26:27], off offset:256
	s_waitcnt vmcnt(0)
	v_and_b32_e32 v33, 0xffff0000, v28
	v_lshlrev_b32_e32 v32, 16, v28
	v_pk_add_f32 v[22:23], v[22:23], v[32:33]
	v_and_b32_e32 v33, 0xffff0000, v30
	v_lshlrev_b32_e32 v32, 16, v30
	v_pk_add_f32 v[18:19], v[18:19], v[32:33]
	v_and_b32_e32 v33, 0xffff0000, v29
	v_lshlrev_b32_e32 v32, 16, v29
	v_and_b32_e32 v29, 0xffff0000, v31
	v_lshlrev_b32_e32 v28, 16, v31
	v_pk_add_f32 v[24:25], v[24:25], v[32:33]
	v_pk_add_f32 v[20:21], v[20:21], v[28:29]
.LBB0_1708:
	v_cvt_pk_bf16_f32 v22, v22, v23
	v_cvt_pk_bf16_f32 v23, v24, v25
	v_cvt_pk_bf16_f32 v24, v18, v19
	v_add_u32_e32 v18, 0xb0, v142
	v_cvt_pk_bf16_f32 v25, v20, v21
	global_store_dwordx4 v[26:27], v[22:25], off offset:256
	v_ashrrev_i32_e32 v19, 31, v18
	v_lshlrev_b64 v[20:21], 12, v[18:19]
	v_mov_b64_e32 v[22:23], s[68:69]
	v_mad_i64_i32 v[18:19], s[22:23], v18, s33, v[22:23]
	v_lshl_add_u64 v[18:19], v[18:19], 0, s[72:73]
	v_lshl_add_u64 v[18:19], v[18:19], 0, v[140:141]
	v_add_co_u32_e32 v22, vcc, s82, v18
	v_lshl_add_u64 v[26:27], s[70:71], 0, v[20:21]
	s_nop 0
	v_addc_co_u32_e32 v23, vcc, 0, v19, vcc
	v_mov_b32_e32 v22, v224
	v_mov_b32_e32 v23, v225
	v_mov_b32_e32 v24, v226
	v_mov_b32_e32 v25, v227
	s_and_b64 vcc, exec, s[2:3]
	v_and_b32_e32 v21, 0xffff0000, v22
	v_lshlrev_b32_e32 v20, 16, v22
	v_pk_mul_f32 v[14:15], v[14:15], v[20:21]
	v_and_b32_e32 v21, 0xffff0000, v24
	v_lshlrev_b32_e32 v20, 16, v24
	v_pk_mul_f32 v[20:21], v[10:11], v[20:21]
	v_and_b32_e32 v11, 0xffff0000, v23
	v_lshlrev_b32_e32 v10, 16, v23
	v_pk_mul_f32 v[16:17], v[16:17], v[10:11]
	v_and_b32_e32 v11, 0xffff0000, v25
	v_lshlrev_b32_e32 v10, 16, v25
	v_pk_mul_f32 v[12:13], v[12:13], v[10:11]
	v_lshl_add_u64 v[10:11], v[26:27], 0, v[140:141]
	s_cbranch_vccnz .LBB0_1710
	global_load_dwordx4 v[22:25], v[10:11], off
	s_waitcnt vmcnt(0)
	v_and_b32_e32 v27, 0xffff0000, v22
	v_lshlrev_b32_e32 v26, 16, v22
	v_pk_add_f32 v[14:15], v[14:15], v[26:27]
	v_and_b32_e32 v27, 0xffff0000, v24
	v_lshlrev_b32_e32 v26, 16, v24
	v_pk_add_f32 v[20:21], v[20:21], v[26:27]
	v_and_b32_e32 v27, 0xffff0000, v23
	v_lshlrev_b32_e32 v26, 16, v23
	v_and_b32_e32 v23, 0xffff0000, v25
	v_lshlrev_b32_e32 v22, 16, v25
	v_pk_add_f32 v[16:17], v[16:17], v[26:27]
	v_pk_add_f32 v[12:13], v[12:13], v[22:23]
.LBB0_1710:
	v_lshl_add_u64 v[18:19], v[18:19], 0, s[76:77]
	v_cvt_pk_bf16_f32 v14, v14, v15
	v_cvt_pk_bf16_f32 v15, v16, v17
	v_cvt_pk_bf16_f32 v16, v20, v21
	v_cvt_pk_bf16_f32 v17, v12, v13
	v_mov_b32_e32 v18, v232
	v_mov_b32_e32 v19, v233
	v_mov_b32_e32 v20, v234
	v_mov_b32_e32 v21, v235
	s_and_b64 vcc, exec, s[2:3]
	global_store_dwordx4 v[10:11], v[14:17], off
	v_and_b32_e32 v13, 0xffff0000, v18
	v_lshlrev_b32_e32 v12, 16, v18
	v_and_b32_e32 v15, 0xffff0000, v20
	v_lshlrev_b32_e32 v14, 16, v20
	v_and_b32_e32 v17, 0xffff0000, v19
	v_lshlrev_b32_e32 v16, 16, v19
	v_and_b32_e32 v19, 0xffff0000, v21
	v_lshlrev_b32_e32 v18, 16, v21
	v_pk_mul_f32 v[6:7], v[6:7], v[12:13]
	v_pk_mul_f32 v[2:3], v[2:3], v[14:15]
	v_pk_mul_f32 v[8:9], v[8:9], v[16:17]
	v_pk_mul_f32 v[4:5], v[4:5], v[18:19]
	s_cbranch_vccnz .LBB0_1712
	global_load_dwordx4 v[12:15], v[10:11], off offset:256
	s_waitcnt vmcnt(0)
	v_and_b32_e32 v17, 0xffff0000, v12
	v_lshlrev_b32_e32 v16, 16, v12
	v_pk_add_f32 v[6:7], v[6:7], v[16:17]
	v_and_b32_e32 v17, 0xffff0000, v14
	v_lshlrev_b32_e32 v16, 16, v14
	v_pk_add_f32 v[2:3], v[2:3], v[16:17]
	v_and_b32_e32 v17, 0xffff0000, v13
	v_lshlrev_b32_e32 v16, 16, v13
	v_and_b32_e32 v13, 0xffff0000, v15
	v_lshlrev_b32_e32 v12, 16, v15
	v_pk_add_f32 v[8:9], v[8:9], v[16:17]
	v_pk_add_f32 v[4:5], v[4:5], v[12:13]
